# chain CUs take 4 tiles, CUs 32-95 take a tenth; retention cross step LDS reads pipelined; two compiler vmcnt(0) removed/hoisted in retention loop
# baseline (speedup 1.0000x reference)
; #define RET_FRESH() int tid = tid0; asm volatile("" : "+v"(tid)); const int lane = tid & 63, r = lane & 31, h = lane >> 5; (void)r; (void)h; (void)tid
; #define RET_VMWAIT() asm volatile("s_waitcnt vmcnt(0)" ::: "memory")
; #define P (*({ CParams* q_ = kp; asm volatile("" : "+s"(q_)); q_; }))
; DI void ret_unit(CParams& P, int l, int u, LAS unsigned char* lds, int tid_, int lane_, int wave_) {
;     ...
;     const float g64 = exp2f(64.f * log2f(1.f - exp2f(-5.f - (float)hh)));
;     const float* ng = P.ret_ng + l * GW + hh * 256; const float* nbp = P.ret_nb + l * GW + hh * 256;
;     f32x16 St[8];
; #pragma unroll
;     for (int i = 0; i < 8; ++i) St[i] = zero16();
;     ...
;     { RET_FRESH(); RET_DMA(0, 0); RET_DMA(1, 0); RET_DMA(2, 0); }
;     RET_VMWAIT();
;     __syncthreads();
;     for (int n = 0; n < 32; ++n) {
;         const int rowbase = b * SEQ + n * 64;
;         const bf16_t* proj = (const bf16_t*)(P.ws + WS_PROJ) + (size_t)rowbase * NPROJ;
;         bf16_t* y = (bf16_t*)(P.ws + WS_Y) + (size_t)rowbase * DM;
;         f32x16 C[2]; C[0] = zero16(); C[1] = zero16();
;     ...
;         const f32x4 gn = *(const f32x4*)(ng + 4 * lane), gb = *(const f32x4*)(nbp + 4 * lane);
.LBB0_388:
	s_lshl_b32 s96, s62, 10
	s_lshl_b64 s[2:3], s[96:97], 2
	s_waitcnt lgkmcnt(0)
	s_add_u32 s17, s10, s2
	s_addc_u32 s19, s11, s3
	s_add_u32 s2, s8, s2
	v_readlane_b32 s8, v255, 10
	s_addc_u32 s3, s9, s3
	s_lshl_b32 s8, s8, 2
	s_add_u32 s10, s2, s8
	s_addc_u32 s11, s3, 0
	s_add_u32 s18, s17, s8
	s_addc_u32 s19, s19, 0
	s_add_u32 s2, s14, s16
	v_writelane_b32 v255, s2, 38
	s_addc_u32 s2, s15, 0
	s_cmp_lt_i32 s0, 4
	v_writelane_b32 v255, s2, 39
	s_cselect_b64 s[20:21], -1, 0
	s_ashr_i32 s2, s1, 7
	s_bfe_u32 s3, s1, 0x10006
	s_cmp_le_i32 s3, s2
	s_cselect_b64 s[8:9], -1, 0
	v_writelane_b32 v255, s8, 40
	s_waitcnt vmcnt(0)
	s_lshl_b32 s91, s2, 5
	s_add_i32 s23, 0, 0x10800
	v_writelane_b32 v255, s9, 41
	s_lshl_b32 s8, s0, 3
	s_ashr_i32 s9, s8, 31
	s_mul_hi_i32 s69, s8, 0x6000
	s_or_b32 s26, s8, 1
	s_or_b32 s28, s8, 2
	s_or_b32 s30, s8, 3
	s_or_b32 s34, s8, 4
	s_or_b32 s36, s8, 5
	s_or_b32 s38, s8, 6
	s_or_b32 s40, s8, 7
	s_lshl_b64 s[24:25], s[8:9], 13
	s_add_i32 s8, s22, 0
	v_readlane_b32 s2, v255, 8
	v_writelane_b32 v255, s8, 42
	s_add_i32 s8, s8, 0x8400
	s_andn2_b32 s1, s1, 63
	s_lshl_b32 s68, s0, 12
	s_ashr_i32 s27, s26, 31
	s_ashr_i32 s29, s28, 31
	s_ashr_i32 s31, s30, 31
	s_ashr_i32 s35, s34, 31
	s_ashr_i32 s37, s36, 31
	s_ashr_i32 s39, s38, 31
	s_ashr_i32 s41, s40, 31
	v_writelane_b32 v255, s8, 43
	s_add_i32 s8, s23, s22
	v_mov_b32_e32 v0, 0
	s_lshl_b32 s96, s3, 5
	s_add_i32 s83, s23, s1
	s_add_i32 s92, s2, s1
	s_add_i32 s49, s2, s68
	s_mul_i32 s80, s0, 0x30000
	s_mul_hi_i32 s3, s26, 0x6000
	s_mul_i32 s73, s26, 0x6000
	s_mul_hi_i32 s74, s28, 0x6000
	s_mul_i32 s75, s28, 0x6000
	s_mul_hi_i32 s47, s30, 0x6000
	s_mul_i32 s78, s30, 0x6000
	s_mul_hi_i32 s54, s34, 0x6000
	s_mul_i32 s72, s34, 0x6000
	s_mul_hi_i32 s1, s36, 0x6000
	s_mul_i32 s0, s36, 0x6000
	s_mul_hi_i32 s62, s38, 0x6000
	s_mul_i32 s63, s38, 0x6000
	s_mul_hi_i32 s46, s40, 0x6000
	s_mul_i32 s44, s40, 0x6000
	s_lshl_b32 s76, s26, 9
	s_lshl_b64 s[26:27], s[26:27], 13
	s_lshl_b32 s77, s28, 9
	s_lshl_b64 s[28:29], s[28:29], 13
	s_lshl_b32 s17, s30, 9
	s_lshl_b64 s[30:31], s[30:31], 13
	s_lshl_b32 s2, s34, 9
	s_lshl_b64 s[34:35], s[34:35], 13
	s_lshl_b32 s42, s36, 9
	s_lshl_b64 s[36:37], s[36:37], 13
	s_lshl_b32 s48, s38, 9
	s_lshl_b64 s[38:39], s[38:39], 13
	s_lshl_b32 s58, s40, 9
	s_lshl_b64 s[40:41], s[40:41], 13
	v_writelane_b32 v255, s8, 44
	s_mov_b32 s22, 0
	v_mov_b32_e32 v1, v0
	v_mov_b32_e32 v2, v0
	v_mov_b32_e32 v3, v0
	v_mov_b32_e32 v4, v0
	v_mov_b32_e32 v5, v0
	v_mov_b32_e32 v6, v0
	v_mov_b32_e32 v7, v0
	v_mov_b32_e32 v8, v0
	v_mov_b32_e32 v9, v0
	v_mov_b32_e32 v10, v0
	v_mov_b32_e32 v11, v0
	v_mov_b32_e32 v12, v0
	v_mov_b32_e32 v13, v0
	v_mov_b32_e32 v14, v0
	v_mov_b32_e32 v15, v0
	v_mov_b32_e32 v16, v0
	v_mov_b32_e32 v17, v0
	v_mov_b32_e32 v18, v0
	v_mov_b32_e32 v19, v0
	v_mov_b32_e32 v20, v0
	v_mov_b32_e32 v21, v0
	v_mov_b32_e32 v22, v0
	v_mov_b32_e32 v23, v0
	v_mov_b32_e32 v24, v0
	v_mov_b32_e32 v25, v0
	v_mov_b32_e32 v26, v0
	v_mov_b32_e32 v27, v0
	v_mov_b32_e32 v28, v0
	v_mov_b32_e32 v29, v0
	v_mov_b32_e32 v30, v0
	v_mov_b32_e32 v31, v0
	v_mov_b32_e32 v32, v0
	v_mov_b32_e32 v33, v0
	v_mov_b32_e32 v34, v0
	v_mov_b32_e32 v35, v0
	v_mov_b32_e32 v36, v0
	v_mov_b32_e32 v37, v0
	v_mov_b32_e32 v38, v0
	v_mov_b32_e32 v39, v0
	v_mov_b32_e32 v40, v0
	v_mov_b32_e32 v41, v0
	v_mov_b32_e32 v42, v0
	v_mov_b32_e32 v43, v0
	v_mov_b32_e32 v44, v0
	v_mov_b32_e32 v45, v0
	v_mov_b32_e32 v46, v0
	v_mov_b32_e32 v47, v0
	v_mov_b32_e32 v48, v0
	v_mov_b32_e32 v49, v0
	v_mov_b32_e32 v50, v0
	v_mov_b32_e32 v51, v0
	v_mov_b32_e32 v52, v0
	v_mov_b32_e32 v53, v0
	v_mov_b32_e32 v54, v0
	v_mov_b32_e32 v55, v0
	v_mov_b32_e32 v56, v0
	v_mov_b32_e32 v57, v0
	v_mov_b32_e32 v58, v0
	v_mov_b32_e32 v59, v0
	v_mov_b32_e32 v60, v0
	v_mov_b32_e32 v61, v0
	v_mov_b32_e32 v62, v0
	v_mov_b32_e32 v63, v0
	v_mov_b32_e32 v64, v0
	v_mov_b32_e32 v65, v0
	v_mov_b32_e32 v66, v0
	v_mov_b32_e32 v67, v0
	v_mov_b32_e32 v68, v0
	v_mov_b32_e32 v69, v0
	v_mov_b32_e32 v70, v0
	v_mov_b32_e32 v71, v0
	v_mov_b32_e32 v72, v0
	v_mov_b32_e32 v73, v0
	v_mov_b32_e32 v74, v0
	v_mov_b32_e32 v75, v0
	v_mov_b32_e32 v76, v0
	v_mov_b32_e32 v77, v0
	v_mov_b32_e32 v78, v0
	v_mov_b32_e32 v79, v0
	v_mov_b32_e32 v80, v0
	v_mov_b32_e32 v81, v0
	v_mov_b32_e32 v82, v0
	v_mov_b32_e32 v83, v0
	v_mov_b32_e32 v84, v0
	v_mov_b32_e32 v85, v0
	v_mov_b32_e32 v86, v0
	v_mov_b32_e32 v87, v0
	v_mov_b32_e32 v88, v0
	v_mov_b32_e32 v89, v0
	v_mov_b32_e32 v90, v0
	v_mov_b32_e32 v91, v0
	v_mov_b32_e32 v92, v0
	v_mov_b32_e32 v93, v0
	v_mov_b32_e32 v94, v0
	v_mov_b32_e32 v95, v0
	v_mov_b32_e32 v96, v0
	v_mov_b32_e32 v97, v0
	v_mov_b32_e32 v98, v0
	v_mov_b32_e32 v99, v0
	v_mov_b32_e32 v100, v0
	v_mov_b32_e32 v101, v0
	v_mov_b32_e32 v102, v0
	v_mov_b32_e32 v103, v0
	v_mov_b32_e32 v104, v0
	v_mov_b32_e32 v105, v0
	v_mov_b32_e32 v106, v0
	v_mov_b32_e32 v107, v0
	v_mov_b32_e32 v108, v0
	v_mov_b32_e32 v109, v0
	v_mov_b32_e32 v110, v0
	v_mov_b32_e32 v111, v0
	v_mov_b32_e32 v112, v0
	v_mov_b32_e32 v113, v0
	v_mov_b32_e32 v114, v0
	v_mov_b32_e32 v115, v0
	v_mov_b32_e32 v116, v0
	v_mov_b32_e32 v117, v0
	v_mov_b32_e32 v118, v0
	v_mov_b32_e32 v119, v0
	v_mov_b32_e32 v120, v0
	v_mov_b32_e32 v121, v0
	v_mov_b32_e32 v122, v0
	v_mov_b32_e32 v123, v0
	v_mov_b32_e32 v124, v0
	v_mov_b32_e32 v125, v0
	v_mov_b32_e32 v126, v0
	v_mov_b32_e32 v127, v0
	v_and_b32_e32 v248, 63, v180
	v_lshlrev_b32_e32 v248, 4, v248
	global_load_dwordx4 v[240:243], v248, s[10:11]
	global_load_dwordx4 v[244:247], v248, s[18:19]
	s_waitcnt vmcnt(0)
	s_barrier
	s_branch .LBB0_390
; #define LAS __attribute__((address_space(3)))
; DI float bflo(unsigned w) { return __uint_as_float(w << 16); }
; DI float bfhi(unsigned w) { return __uint_as_float(w & 0xffff0000u); }
; #define wave (__builtin_amdgcn_readfirstlane(tid >> 6))
; DI void ret_unit(CParams& P, int l, int u, LAS unsigned char* lds, int tid_, int lane_, int wave_) {
;     ...
;         float ps[8], pss[8];
; #pragma unroll
;         for (int i = 0; i < 8; ++i) { const u32x2 w = *(const LAS u32x2*)(R + (wave * 8 + i) * LDR + 4 * lane); const float v0 = bflo(w.x), v1 = bfhi(w.x), v2 = bflo(w.y), v3 = bfhi(w.y);
;             ps[i] = (v0 + v1) + (v2 + v3); pss[i] = (v0 * v0 + v1 * v1) + (v2 * v2 + v3 * v3); }
;         const float S1 = reduce8(ps, lane), S2 = reduce8(pss, lane);
.LBB0_389:
	v_mov_b32_e32 v181, v180
	v_and_b32_e32 v229, 64, v226
	v_and_b32_e32 v193, 63, v181
	v_lshlrev_b32_e32 v196, 3, v193
	v_add_u32_e32 v186, s49, v196
	ds_read2st64_b64 v[128:131], v186 offset1:1
	ds_read2st64_b64 v[132:135], v186 offset0:2 offset1:3
	v_xor_b32_e32 v228, 32, v226
	v_add_u32_e32 v229, 64, v229
	v_cmp_lt_i32_e32 vcc, v228, v229
	s_waitcnt lgkmcnt(0)
	v_lshlrev_b32_e32 v145, 16, v128
	v_and_b32_e32 v147, 0xffff0000, v128
	v_lshlrev_b32_e32 v149, 16, v129
	v_and_b32_e32 v151, 0xffff0000, v129
	v_lshlrev_b32_e32 v153, 16, v130
	v_and_b32_e32 v155, 0xffff0000, v130
	v_lshlrev_b32_e32 v165, 16, v131
	v_and_b32_e32 v167, 0xffff0000, v131
	ds_read2st64_b64 v[128:131], v186 offset0:4 offset1:5
	v_mul_f32_e32 v144, v145, v145
	v_mul_f32_e32 v146, v147, v147
	v_mul_f32_e32 v148, v149, v149
	v_mul_f32_e32 v150, v151, v151
	v_lshlrev_b32_e32 v169, 16, v132
	v_and_b32_e32 v171, 0xffff0000, v132
	v_lshlrev_b32_e32 v173, 16, v133
	v_and_b32_e32 v175, 0xffff0000, v133
	v_lshlrev_b32_e32 v177, 16, v134
	v_and_b32_e32 v179, 0xffff0000, v134
	v_lshlrev_b32_e32 v183, 16, v135
	v_and_b32_e32 v185, 0xffff0000, v135
	ds_read2st64_b64 v[132:135], v186 offset0:6 offset1:7
	v_mul_f32_e32 v152, v153, v153
	v_mul_f32_e32 v154, v155, v155
	v_mul_f32_e32 v164, v165, v165
	v_mul_f32_e32 v166, v167, v167
	v_pk_add_f32 v[144:145], v[144:145], v[146:147]
	v_pk_add_f32 v[146:147], v[148:149], v[150:151]
	v_mul_f32_e32 v168, v169, v169
	v_mul_f32_e32 v170, v171, v171
	v_mul_f32_e32 v172, v173, v173
	v_mul_f32_e32 v174, v175, v175
	v_pk_add_f32 v[144:145], v[144:145], v[146:147]
	v_pk_add_f32 v[146:147], v[152:153], v[154:155]
	v_pk_add_f32 v[148:149], v[164:165], v[166:167]
	v_mul_f32_e32 v176, v177, v177
	v_mul_f32_e32 v178, v179, v179
	v_mul_f32_e32 v182, v183, v183
	v_mul_f32_e32 v184, v185, v185
	s_waitcnt lgkmcnt(0)
	v_lshlrev_b32_e32 v187, 16, v128
	v_and_b32_e32 v189, 0xffff0000, v128
	v_lshlrev_b32_e32 v191, 16, v129
	v_and_b32_e32 v129, 0xffff0000, v129
	v_pk_add_f32 v[146:147], v[146:147], v[148:149]
	v_pk_add_f32 v[148:149], v[168:169], v[170:171]
	v_pk_add_f32 v[150:151], v[172:173], v[174:175]
	v_mul_f32_e32 v186, v187, v187
	v_mul_f32_e32 v188, v189, v189
	v_mul_f32_e32 v190, v191, v191
	v_mul_f32_e32 v128, v129, v129
	v_lshlrev_b32_e32 v199, 16, v130
	v_and_b32_e32 v201, 0xffff0000, v130
	v_lshlrev_b32_e32 v203, 16, v131
	v_and_b32_e32 v131, 0xffff0000, v131
	v_pk_add_f32 v[148:149], v[148:149], v[150:151]
	v_pk_add_f32 v[150:151], v[176:177], v[178:179]
	v_pk_add_f32 v[152:153], v[182:183], v[184:185]
	v_mul_f32_e32 v198, v199, v199
	v_mul_f32_e32 v200, v201, v201
	v_mul_f32_e32 v202, v203, v203
	v_mul_f32_e32 v130, v131, v131
	v_lshlrev_b32_e32 v205, 16, v132
	v_and_b32_e32 v207, 0xffff0000, v132
	v_lshlrev_b32_e32 v209, 16, v133
	v_and_b32_e32 v133, 0xffff0000, v133
	v_xor_b32_e32 v230, 16, v226
	v_pk_add_f32 v[150:151], v[150:151], v[152:153]
	v_pk_add_f32 v[152:153], v[186:187], v[188:189]
	v_pk_add_f32 v[128:129], v[190:191], v[128:129]
	v_mul_f32_e32 v204, v205, v205
	v_mul_f32_e32 v206, v207, v207
	v_mul_f32_e32 v208, v209, v209
	v_mul_f32_e32 v132, v133, v133
	v_lshlrev_b32_e32 v211, 16, v134
	v_and_b32_e32 v213, 0xffff0000, v134
	v_lshlrev_b32_e32 v215, 16, v135
	v_and_b32_e32 v135, 0xffff0000, v135
	v_cndmask_b32_e32 v228, v226, v228, vcc
	v_cmp_lt_i32_e32 vcc, v230, v229
	v_xor_b32_e32 v231, 8, v226
	v_pk_add_f32 v[128:129], v[152:153], v[128:129]
	v_pk_add_f32 v[152:153], v[198:199], v[200:201]
	v_pk_add_f32 v[130:131], v[202:203], v[130:131]
	v_mul_f32_e32 v210, v211, v211
	v_mul_f32_e32 v212, v213, v213
	v_mul_f32_e32 v214, v215, v215
	v_mul_f32_e32 v134, v135, v135
	v_and_b32_e32 v216, 32, v181
	v_cndmask_b32_e32 v230, v226, v230, vcc
	v_cmp_lt_i32_e32 vcc, v231, v229
	v_pk_add_f32 v[130:131], v[152:153], v[130:131]
	v_pk_add_f32 v[152:153], v[204:205], v[206:207]
	v_pk_add_f32 v[132:133], v[208:209], v[132:133]
	v_cndmask_b32_e32 v231, v226, v231, vcc
	v_pk_add_f32 v[132:133], v[152:153], v[132:133]
	v_pk_add_f32 v[152:153], v[210:211], v[212:213]
	v_pk_add_f32 v[134:135], v[214:215], v[134:135]
	v_cmp_eq_u32_e32 vcc, 0, v216
	v_lshlrev_b32_e32 v228, 2, v228
	v_pk_add_f32 v[134:135], v[152:153], v[134:135]
	v_cndmask_b32_e32 v152, v145, v129, vcc
	ds_bpermute_b32 v153, v228, v152
	v_cndmask_b32_e32 v152, v147, v131, vcc
	ds_bpermute_b32 v155, v228, v152
	v_cndmask_b32_e32 v152, v149, v133, vcc
	ds_bpermute_b32 v165, v228, v152
	v_cndmask_b32_e32 v152, v151, v135, vcc
	ds_bpermute_b32 v167, v228, v152
	v_cndmask_b32_e32 v152, v144, v128, vcc
	ds_bpermute_b32 v152, v228, v152
	v_cndmask_b32_e32 v129, v129, v145, vcc
	v_cndmask_b32_e32 v145, v148, v132, vcc
	ds_bpermute_b32 v164, v228, v145
	v_cndmask_b32_e32 v128, v128, v144, vcc
	v_and_b32_e32 v217, 16, v181
	s_waitcnt lgkmcnt(0)
	v_pk_add_f32 v[144:145], v[128:129], v[152:153]
	v_cndmask_b32_e32 v129, v133, v149, vcc
	v_cndmask_b32_e32 v128, v132, v148, vcc
	v_pk_add_f32 v[148:149], v[128:129], v[164:165]
	v_cmp_eq_u32_e64 s[8:9], 0, v217
	v_lshlrev_b32_e32 v230, 2, v230
	v_cndmask_b32_e32 v129, v131, v147, vcc
	v_cndmask_b32_e64 v128, v145, v149, s[8:9]
	ds_bpermute_b32 v153, v230, v128
	v_cndmask_b32_e32 v128, v146, v130, vcc
	ds_bpermute_b32 v154, v228, v128
	v_cndmask_b32_e32 v128, v150, v134, vcc
	ds_bpermute_b32 v166, v228, v128
	v_cndmask_b32_e32 v128, v130, v146, vcc
	v_lshlrev_b32_e32 v132, 4, v193
	s_waitcnt lgkmcnt(0)
; #define LAS __attribute__((address_space(3)))
; DI float bflo(unsigned w) { return __uint_as_float(w << 16); }
; DI float bfhi(unsigned w) { return __uint_as_float(w & 0xffff0000u); }
; DI unsigned pk2(float lo, float hi) { f32x2 v = {lo, hi}; bf16v2 b = __builtin_convertvector(v, bf16v2); return __builtin_bit_cast(unsigned, b); }
; DI float silu_f(float x) { return x * __builtin_amdgcn_rcpf(1.f + __expf(-x)); }
; DI float bcast_lane(float v, int srclane) { return __uint_as_float(__builtin_amdgcn_readlane(__float_as_uint(v), srclane)); }
; #define wave (__builtin_amdgcn_readfirstlane(tid >> 6))
; DI void ret_unit(CParams& P, int l, int u, LAS unsigned char* lds, int tid_, int lane_, int wave_) {
;     ...
;         const float S1 = reduce8(ps, lane), S2 = reduce8(pss, lane);
;         const float mean_l = S1 * (1.f / 256.f), var_l = S2 * (1.f / 256.f) - mean_l * mean_l, rstd_l = rsqrtf(fmaxf(var_l, 0.f) + EPS);
;         const f32x4 gn = *(const f32x4*)(ng + 4 * lane), gb = *(const f32x4*)(nbp + 4 * lane);
; #pragma unroll
;         for (int i = 0; i < 8; ++i) { const float mean = bcast_lane(mean_l, 8 * i), rstd = bcast_lane(rstd_l, 8 * i);
;             const u32x2 w2 = *(const LAS u32x2*)(R + (wave * 8 + i) * LDR + 4 * lane); const float v0 = bflo(w2.x), v1 = bfhi(w2.x), v2 = bflo(w2.y), v3 = bfhi(w2.y);
;             const float g0 = bflo(gate[i].x), g1 = bfhi(gate[i].x), g2 = bflo(gate[i].y), g3 = bfhi(gate[i].y);
;             const float o0 = ((v0 - mean) * rstd * gn.x + gb.x) * silu_f(g0), o1 = ((v1 - mean) * rstd * gn.y + gb.y) * silu_f(g1);
;             const float o2 = ((v2 - mean) * rstd * gn.z + gb.z) * silu_f(g2), o3 = ((v3 - mean) * rstd * gn.w + gb.w) * silu_f(g3);
;             u32x2 w; w.x = pk2(o0, o1); w.y = pk2(o2, o3); *(u32x2*)(y + (size_t)(wave * 8 + i) * DM + 2048 + hh * 256 + 4 * lane) = w; }
	v_pk_add_f32 v[146:147], v[128:129], v[154:155]
	v_cndmask_b32_e32 v129, v135, v151, vcc
	v_cndmask_b32_e32 v128, v134, v150, vcc
	v_pk_add_f32 v[150:151], v[128:129], v[166:167]
	v_cndmask_b32_e64 v152, v144, v148, s[8:9]
	v_cndmask_b32_e64 v128, v147, v151, s[8:9]
	ds_bpermute_b32 v155, v230, v128
	v_mov_b64_e32 v[128:129], v[240:241]
	v_mov_b64_e32 v[130:131], v[242:243]
	v_mov_b64_e32 v[132:133], v[244:245]
	v_mov_b64_e32 v[134:135], v[246:247]
	v_cndmask_b32_e64 v145, v149, v145, s[8:9]
	v_cndmask_b32_e64 v149, v146, v150, s[8:9]
	ds_bpermute_b32 v152, v230, v152
	ds_bpermute_b32 v154, v230, v149
	v_and_b32_e32 v181, 8, v181
	v_cndmask_b32_e64 v144, v148, v144, s[8:9]
	v_cndmask_b32_e64 v147, v151, v147, s[8:9]
	v_cndmask_b32_e64 v146, v150, v146, s[8:9]
	s_waitcnt lgkmcnt(0)
	v_pk_add_f32 v[144:145], v[144:145], v[152:153]
	v_pk_add_f32 v[146:147], v[146:147], v[154:155]
	v_cmp_eq_u32_e32 vcc, 0, v181
	v_lshlrev_b32_e32 v231, 2, v231
	v_xor_b32_e32 v232, 4, v226
	v_cndmask_b32_e32 v148, v145, v147, vcc
	ds_bpermute_b32 v149, v231, v148
	v_cndmask_b32_e32 v148, v144, v146, vcc
	ds_bpermute_b32 v148, v231, v148
	v_cmp_lt_i32_e64 s[8:9], v232, v229
	v_cndmask_b32_e32 v145, v147, v145, vcc
	v_cndmask_b32_e32 v144, v146, v144, vcc
	v_cndmask_b32_e64 v150, v226, v232, s[8:9]
	v_lshlrev_b32_e32 v150, 2, v150
	s_waitcnt lgkmcnt(0)
	v_pk_add_f32 v[144:145], v[144:145], v[148:149]
	ds_bpermute_b32 v147, v150, v145
	ds_bpermute_b32 v146, v150, v144
	v_xor_b32_e32 v148, 2, v226
	v_cmp_lt_i32_e32 vcc, v148, v229
	s_lshl_b64 s[8:9], s[64:65], 14
	s_sub_u32 s64, 0, s8
	v_cndmask_b32_e32 v148, v226, v148, vcc
	v_lshlrev_b32_e32 v148, 2, v148
	s_waitcnt lgkmcnt(0)
	v_pk_add_f32 v[144:145], v[144:145], v[146:147]
	ds_bpermute_b32 v147, v148, v145
	ds_bpermute_b32 v146, v148, v144
	v_xor_b32_e32 v148, 1, v226
	v_cmp_lt_i32_e32 vcc, v148, v229
	s_mov_b32 s8, 0x3b800000
	v_lshlrev_b32_e32 v166, 16, v162
	v_cndmask_b32_e32 v148, v226, v148, vcc
	v_lshlrev_b32_e32 v148, 2, v148
	s_waitcnt lgkmcnt(0)
	v_pk_add_f32 v[144:145], v[144:145], v[146:147]
	ds_bpermute_b32 v147, v148, v145
	ds_bpermute_b32 v146, v148, v144
	v_and_b32_e32 v167, 0xffff0000, v162
	v_mul_f32_e32 v162, 0xbfb8aa3b, v167
	v_exp_f32_e32 v162, v162
	s_waitcnt lgkmcnt(0)
	v_pk_add_f32 v[144:145], v[144:145], v[146:147]
	s_nop 0
	v_pk_mul_f32 v[144:145], v[144:145], s[8:9] op_sel_hi:[1,0]
	s_subb_u32 s8, 0, s9
	v_fma_f32 v144, -v145, v145, v144
	v_max_f32_e32 v144, 0, v144
	v_add_f32_e32 v144, 0x358637bd, v144
	v_mul_f32_e32 v146, 0x4b800000, v144
	v_cmp_gt_f32_e32 vcc, s45, v144
	s_add_u32 s9, s23, s64
	s_addc_u32 s23, s90, s8
	v_cndmask_b32_e32 v144, v144, v146, vcc
	v_rsq_f32_e32 v144, v144
	v_readlane_b32 s8, v255, 8
	v_mul_f32_e32 v146, 0x45800000, v144
	v_cndmask_b32_e32 v144, v144, v146, vcc
	v_add_u32_e32 v146, s8, v196
	v_add_u32_e32 v147, s68, v146
	ds_read_b64 v[148:149], v147
	v_add_u32_e32 v147, s76, v146
	v_add_u32_e32 v152, s77, v146
	v_add_u32_e32 v154, s17, v146
	ds_read_b64 v[150:151], v147
	ds_read_b64 v[152:153], v152
	ds_read_b64 v[154:155], v154
	v_mul_f32_e32 v147, 0xbfb8aa3b, v166
	v_exp_f32_e32 v147, v147
	v_readlane_b32 s8, v145, 0
	s_waitcnt lgkmcnt(3)
	v_lshlrev_b32_e32 v164, 16, v148
	v_and_b32_e32 v165, 0xffff0000, v148
	v_add_f32_e32 v147, 1.0, v147
	v_rcp_f32_e32 v168, v147
	v_add_f32_e32 v147, 1.0, v162
	v_rcp_f32_e32 v169, v147
	v_readlane_b32 s64, v144, 0
	v_pk_add_f32 v[164:165], v[164:165], s[8:9] op_sel_hi:[1,0] neg_lo:[0,1] neg_hi:[0,1]
	v_lshlrev_b32_e32 v162, 16, v163
	v_pk_mul_f32 v[164:165], s[64:65], v[164:165] op_sel_hi:[0,1]
	v_pk_fma_f32 v[164:165], v[128:129], v[164:165], v[132:133]
	v_pk_mul_f32 v[166:167], v[168:169], v[166:167]
	v_and_b32_e32 v163, 0xffff0000, v163
	v_mul_f32_e32 v147, 0xbfb8aa3b, v162
	v_pk_mul_f32 v[164:165], v[166:167], v[164:165]
	v_exp_f32_e32 v147, v147
	v_mul_f32_e32 v166, 0xbfb8aa3b, v163
	v_exp_f32_e32 v167, v166
	v_lshlrev_b32_e32 v148, 16, v149
	v_add_f32_e32 v147, 1.0, v147
	v_rcp_f32_e32 v166, v147
	v_add_f32_e32 v147, 1.0, v167
	v_rcp_f32_e32 v167, v147
	v_and_b32_e32 v149, 0xffff0000, v149
	v_pk_add_f32 v[148:149], v[148:149], s[8:9] op_sel_hi:[1,0] neg_lo:[0,1] neg_hi:[0,1]
	s_add_u32 s8, s9, s24
	v_pk_mul_f32 v[148:149], s[64:65], v[148:149] op_sel_hi:[0,1]
	s_addc_u32 s65, s23, s25
	v_pk_fma_f32 v[148:149], v[130:131], v[148:149], v[134:135]
	v_pk_mul_f32 v[162:163], v[166:167], v[162:163]
	s_add_u32 s64, s8, s16
	v_pk_mul_f32 v[148:149], v[162:163], v[148:149]
	s_addc_u32 s65, s65, 0
	v_cvt_pk_bf16_f32 v163, v148, v149
	v_lshl_add_u64 v[148:149], s[64:65], 0, v[196:197]
	v_add_co_u32_e32 v148, vcc, s57, v148
	v_cvt_pk_bf16_f32 v162, v164, v165
	s_nop 0
	v_addc_co_u32_e32 v149, vcc, 0, v149, vcc
	global_store_dwordx2 v[148:149], v[162:163], off
	v_lshlrev_b32_e32 v162, 16, v160
	v_and_b32_e32 v163, 0xffff0000, v160
	v_mul_f32_e32 v147, 0xbfb8aa3b, v162
	v_exp_f32_e32 v147, v147
	v_mul_f32_e32 v149, 0xbfb8aa3b, v163
	v_exp_f32_e32 v160, v149
	v_readlane_b32 s8, v145, 8
	v_add_f32_e32 v147, 1.0, v147
	v_rcp_f32_e32 v164, v147
	v_add_f32_e32 v147, 1.0, v160
	v_rcp_f32_e32 v165, v147
	s_waitcnt lgkmcnt(2)
; #define LAS __attribute__((address_space(3)))
; DI float bflo(unsigned w) { return __uint_as_float(w << 16); }
; DI float bfhi(unsigned w) { return __uint_as_float(w & 0xffff0000u); }
; DI unsigned pk2(float lo, float hi) { f32x2 v = {lo, hi}; bf16v2 b = __builtin_convertvector(v, bf16v2); return __builtin_bit_cast(unsigned, b); }
; DI float silu_f(float x) { return x * __builtin_amdgcn_rcpf(1.f + __expf(-x)); }
; DI float bcast_lane(float v, int srclane) { return __uint_as_float(__builtin_amdgcn_readlane(__float_as_uint(v), srclane)); }
; #define wave (__builtin_amdgcn_readfirstlane(tid >> 6))
; DI void ret_unit(CParams& P, int l, int u, LAS unsigned char* lds, int tid_, int lane_, int wave_) {
;     ...
; #pragma unroll
;         for (int i = 0; i < 8; ++i) { const float mean = bcast_lane(mean_l, 8 * i), rstd = bcast_lane(rstd_l, 8 * i);
;             const u32x2 w2 = *(const LAS u32x2*)(R + (wave * 8 + i) * LDR + 4 * lane); const float v0 = bflo(w2.x), v1 = bfhi(w2.x), v2 = bflo(w2.y), v3 = bfhi(w2.y);
;             const float g0 = bflo(gate[i].x), g1 = bfhi(gate[i].x), g2 = bflo(gate[i].y), g3 = bfhi(gate[i].y);
;             const float o0 = ((v0 - mean) * rstd * gn.x + gb.x) * silu_f(g0), o1 = ((v1 - mean) * rstd * gn.y + gb.y) * silu_f(g1);
;             const float o2 = ((v2 - mean) * rstd * gn.z + gb.z) * silu_f(g2), o3 = ((v3 - mean) * rstd * gn.w + gb.w) * silu_f(g3);
;             u32x2 w; w.x = pk2(o0, o1); w.y = pk2(o2, o3); *(u32x2*)(y + (size_t)(wave * 8 + i) * DM + 2048 + hh * 256 + 4 * lane) = w; }
	v_lshlrev_b32_e32 v148, 16, v150
	v_and_b32_e32 v149, 0xffff0000, v150
	v_readlane_b32 s64, v144, 8
	v_pk_add_f32 v[148:149], v[148:149], s[8:9] op_sel_hi:[1,0] neg_lo:[0,1] neg_hi:[0,1]
	v_lshlrev_b32_e32 v160, 16, v161
	v_pk_mul_f32 v[148:149], s[64:65], v[148:149] op_sel_hi:[0,1]
	v_pk_fma_f32 v[148:149], v[128:129], v[148:149], v[132:133]
	v_pk_mul_f32 v[162:163], v[164:165], v[162:163]
	v_and_b32_e32 v161, 0xffff0000, v161
	v_mul_f32_e32 v147, 0xbfb8aa3b, v160
	v_pk_mul_f32 v[148:149], v[162:163], v[148:149]
	v_exp_f32_e32 v147, v147
	v_mul_f32_e32 v162, 0xbfb8aa3b, v161
	v_exp_f32_e32 v163, v162
	v_lshlrev_b32_e32 v150, 16, v151
	v_add_f32_e32 v147, 1.0, v147
	v_rcp_f32_e32 v162, v147
	v_add_f32_e32 v147, 1.0, v163
	v_rcp_f32_e32 v163, v147
	v_and_b32_e32 v151, 0xffff0000, v151
	v_pk_add_f32 v[150:151], v[150:151], s[8:9] op_sel_hi:[1,0] neg_lo:[0,1] neg_hi:[0,1]
	s_add_u32 s8, s9, s26
	v_pk_mul_f32 v[150:151], s[64:65], v[150:151] op_sel_hi:[0,1]
	s_addc_u32 s65, s23, s27
	v_pk_fma_f32 v[150:151], v[130:131], v[150:151], v[134:135]
	v_pk_mul_f32 v[160:161], v[162:163], v[160:161]
	s_add_u32 s64, s8, s16
	v_pk_mul_f32 v[150:151], v[160:161], v[150:151]
	s_addc_u32 s65, s65, 0
	v_cvt_pk_bf16_f32 v148, v148, v149
	v_cvt_pk_bf16_f32 v149, v150, v151
	v_lshl_add_u64 v[150:151], s[64:65], 0, v[196:197]
	v_add_co_u32_e32 v150, vcc, s57, v150
	v_readlane_b32 s8, v145, 16
	s_nop 0
	v_addc_co_u32_e32 v151, vcc, 0, v151, vcc
	global_store_dwordx2 v[150:151], v[148:149], off
	v_lshlrev_b32_e32 v150, 16, v158
	v_and_b32_e32 v151, 0xffff0000, v158
	v_mul_f32_e32 v147, 0xbfb8aa3b, v150
	v_exp_f32_e32 v147, v147
	v_mul_f32_e32 v149, 0xbfb8aa3b, v151
	v_exp_f32_e32 v158, v149
	s_waitcnt lgkmcnt(1)
	v_lshlrev_b32_e32 v148, 16, v152
	v_add_f32_e32 v147, 1.0, v147
	v_rcp_f32_e32 v160, v147
	v_add_f32_e32 v147, 1.0, v158
	v_rcp_f32_e32 v161, v147
	v_and_b32_e32 v149, 0xffff0000, v152
	v_readlane_b32 s64, v144, 16
	v_pk_add_f32 v[148:149], v[148:149], s[8:9] op_sel_hi:[1,0] neg_lo:[0,1] neg_hi:[0,1]
	v_lshlrev_b32_e32 v158, 16, v159
	v_pk_mul_f32 v[148:149], s[64:65], v[148:149] op_sel_hi:[0,1]
	v_pk_fma_f32 v[148:149], v[128:129], v[148:149], v[132:133]
	v_pk_mul_f32 v[150:151], v[160:161], v[150:151]
	v_and_b32_e32 v159, 0xffff0000, v159
	v_mul_f32_e32 v147, 0xbfb8aa3b, v158
	v_pk_mul_f32 v[148:149], v[150:151], v[148:149]
	v_exp_f32_e32 v147, v147
	v_mul_f32_e32 v151, 0xbfb8aa3b, v159
	v_exp_f32_e32 v160, v151
	v_lshlrev_b32_e32 v150, 16, v153
	v_add_f32_e32 v147, 1.0, v147
	v_rcp_f32_e32 v152, v147
	v_add_f32_e32 v147, 1.0, v160
	v_and_b32_e32 v151, 0xffff0000, v153
	v_rcp_f32_e32 v153, v147
	v_pk_add_f32 v[150:151], v[150:151], s[8:9] op_sel_hi:[1,0] neg_lo:[0,1] neg_hi:[0,1]
	s_add_u32 s8, s9, s28
	v_pk_mul_f32 v[150:151], s[64:65], v[150:151] op_sel_hi:[0,1]
	s_addc_u32 s65, s23, s29
	v_pk_fma_f32 v[150:151], v[130:131], v[150:151], v[134:135]
	v_pk_mul_f32 v[152:153], v[152:153], v[158:159]
	s_add_u32 s64, s8, s16
	v_pk_mul_f32 v[150:151], v[152:153], v[150:151]
	s_addc_u32 s65, s65, 0
	v_cvt_pk_bf16_f32 v148, v148, v149
	v_cvt_pk_bf16_f32 v149, v150, v151
	v_lshl_add_u64 v[150:151], s[64:65], 0, v[196:197]
	v_add_co_u32_e32 v150, vcc, s57, v150
	v_readlane_b32 s8, v145, 24
	s_nop 0
	v_addc_co_u32_e32 v151, vcc, 0, v151, vcc
	global_store_dwordx2 v[150:151], v[148:149], off
	v_lshlrev_b32_e32 v150, 16, v156
	v_and_b32_e32 v151, 0xffff0000, v156
	v_mul_f32_e32 v147, 0xbfb8aa3b, v150
	v_exp_f32_e32 v147, v147
	v_mul_f32_e32 v149, 0xbfb8aa3b, v151
	v_exp_f32_e32 v153, v149
	s_waitcnt lgkmcnt(0)
	v_lshlrev_b32_e32 v148, 16, v154
	v_add_f32_e32 v147, 1.0, v147
	v_rcp_f32_e32 v152, v147
	v_add_f32_e32 v147, 1.0, v153
	v_rcp_f32_e32 v153, v147
	v_and_b32_e32 v149, 0xffff0000, v154
	v_readlane_b32 s64, v144, 24
	v_pk_add_f32 v[148:149], v[148:149], s[8:9] op_sel_hi:[1,0] neg_lo:[0,1] neg_hi:[0,1]
	v_pk_mul_f32 v[150:151], v[152:153], v[150:151]
	v_pk_mul_f32 v[148:149], s[64:65], v[148:149] op_sel_hi:[0,1]
	v_lshlrev_b32_e32 v152, 16, v157
	v_pk_fma_f32 v[148:149], v[128:129], v[148:149], v[132:133]
	v_and_b32_e32 v153, 0xffff0000, v157
	v_mul_f32_e32 v147, 0xbfb8aa3b, v152
	v_pk_mul_f32 v[148:149], v[150:151], v[148:149]
	v_exp_f32_e32 v147, v147
	v_mul_f32_e32 v151, 0xbfb8aa3b, v153
	v_exp_f32_e32 v156, v151
	v_lshlrev_b32_e32 v150, 16, v155
	v_add_f32_e32 v147, 1.0, v147
	v_rcp_f32_e32 v154, v147
	v_add_f32_e32 v147, 1.0, v156
	v_and_b32_e32 v151, 0xffff0000, v155
	v_rcp_f32_e32 v155, v147
	v_pk_add_f32 v[150:151], v[150:151], s[8:9] op_sel_hi:[1,0] neg_lo:[0,1] neg_hi:[0,1]
	s_add_u32 s8, s9, s30
	v_pk_mul_f32 v[150:151], s[64:65], v[150:151] op_sel_hi:[0,1]
	s_addc_u32 s65, s23, s31
	v_pk_fma_f32 v[150:151], v[130:131], v[150:151], v[134:135]
	v_pk_mul_f32 v[152:153], v[154:155], v[152:153]
	s_add_u32 s64, s8, s16
	v_pk_mul_f32 v[150:151], v[152:153], v[150:151]
	s_addc_u32 s65, s65, 0
	v_lshlrev_b32_e32 v156, 16, v142
	v_cvt_pk_bf16_f32 v148, v148, v149
	v_cvt_pk_bf16_f32 v149, v150, v151
	v_lshl_add_u64 v[150:151], s[64:65], 0, v[196:197]
	v_and_b32_e32 v157, 0xffff0000, v142
	v_mul_f32_e32 v142, 0xbfb8aa3b, v156
	v_add_co_u32_e32 v150, vcc, s57, v150
	v_exp_f32_e32 v142, v142
	v_mul_f32_e32 v155, 0xbfb8aa3b, v157
	v_addc_co_u32_e32 v151, vcc, 0, v151, vcc
	v_add_u32_e32 v147, s2, v146
	v_exp_f32_e32 v159, v155
	global_store_dwordx2 v[150:151], v[148:149], off
	ds_read_b64 v[148:149], v147
	v_add_f32_e32 v142, 1.0, v142
	v_rcp_f32_e32 v158, v142
	v_add_f32_e32 v142, 1.0, v159
	v_rcp_f32_e32 v159, v142
	v_readlane_b32 s8, v145, 32
	s_waitcnt lgkmcnt(0)
; #define LAS __attribute__((address_space(3)))
; DI float bflo(unsigned w) { return __uint_as_float(w << 16); }
; DI float bfhi(unsigned w) { return __uint_as_float(w & 0xffff0000u); }
; DI unsigned pk2(float lo, float hi) { f32x2 v = {lo, hi}; bf16v2 b = __builtin_convertvector(v, bf16v2); return __builtin_bit_cast(unsigned, b); }
; DI float silu_f(float x) { return x * __builtin_amdgcn_rcpf(1.f + __expf(-x)); }
; DI float bcast_lane(float v, int srclane) { return __uint_as_float(__builtin_amdgcn_readlane(__float_as_uint(v), srclane)); }
; #define wave (__builtin_amdgcn_readfirstlane(tid >> 6))
; DI void ret_unit(CParams& P, int l, int u, LAS unsigned char* lds, int tid_, int lane_, int wave_) {
;     ...
; #pragma unroll
;         for (int i = 0; i < 8; ++i) { const float mean = bcast_lane(mean_l, 8 * i), rstd = bcast_lane(rstd_l, 8 * i);
;             const u32x2 w2 = *(const LAS u32x2*)(R + (wave * 8 + i) * LDR + 4 * lane); const float v0 = bflo(w2.x), v1 = bfhi(w2.x), v2 = bflo(w2.y), v3 = bfhi(w2.y);
;             const float g0 = bflo(gate[i].x), g1 = bfhi(gate[i].x), g2 = bflo(gate[i].y), g3 = bfhi(gate[i].y);
;             const float o0 = ((v0 - mean) * rstd * gn.x + gb.x) * silu_f(g0), o1 = ((v1 - mean) * rstd * gn.y + gb.y) * silu_f(g1);
;             const float o2 = ((v2 - mean) * rstd * gn.z + gb.z) * silu_f(g2), o3 = ((v3 - mean) * rstd * gn.w + gb.w) * silu_f(g3);
;             u32x2 w; w.x = pk2(o0, o1); w.y = pk2(o2, o3); *(u32x2*)(y + (size_t)(wave * 8 + i) * DM + 2048 + hh * 256 + 4 * lane) = w; }
	v_lshlrev_b32_e32 v154, 16, v148
	v_and_b32_e32 v155, 0xffff0000, v148
	v_readlane_b32 s64, v144, 32
	v_pk_add_f32 v[154:155], v[154:155], s[8:9] op_sel_hi:[1,0] neg_lo:[0,1] neg_hi:[0,1]
	v_pk_mul_f32 v[156:157], v[158:159], v[156:157]
	v_pk_mul_f32 v[154:155], s[64:65], v[154:155] op_sel_hi:[0,1]
	v_pk_fma_f32 v[154:155], v[128:129], v[154:155], v[132:133]
	v_lshlrev_b32_e32 v142, 16, v149
	v_pk_mul_f32 v[154:155], v[156:157], v[154:155]
	v_lshlrev_b32_e32 v156, 16, v143
	v_and_b32_e32 v157, 0xffff0000, v143
	v_mul_f32_e32 v143, 0xbfb8aa3b, v156
	v_exp_f32_e32 v148, v143
	v_mul_f32_e32 v143, 0xbfb8aa3b, v157
	v_exp_f32_e32 v158, v143
	v_and_b32_e32 v143, 0xffff0000, v149
	v_add_f32_e32 v148, 1.0, v148
	v_rcp_f32_e32 v148, v148
	v_add_f32_e32 v149, 1.0, v158
	v_rcp_f32_e32 v149, v149
	v_pk_add_f32 v[142:143], v[142:143], s[8:9] op_sel_hi:[1,0] neg_lo:[0,1] neg_hi:[0,1]
	s_add_u32 s8, s9, s34
	v_pk_mul_f32 v[142:143], s[64:65], v[142:143] op_sel_hi:[0,1]
	s_addc_u32 s65, s23, s35
	v_pk_fma_f32 v[142:143], v[130:131], v[142:143], v[134:135]
	v_pk_mul_f32 v[148:149], v[148:149], v[156:157]
	s_add_u32 s64, s8, s16
	v_pk_mul_f32 v[142:143], v[148:149], v[142:143]
	s_addc_u32 s65, s65, 0
	v_cvt_pk_bf16_f32 v149, v142, v143
	v_lshl_add_u64 v[142:143], s[64:65], 0, v[196:197]
	v_add_co_u32_e32 v142, vcc, s57, v142
	v_add_u32_e32 v147, s42, v146
	v_add_u32_e32 v150, s48, v146
	v_add_u32_e32 v152, s58, v146
	v_cvt_pk_bf16_f32 v148, v154, v155
	v_addc_co_u32_e32 v143, vcc, 0, v143, vcc
	ds_read_b64 v[146:147], v147
	ds_read_b64 v[150:151], v150
	ds_read_b64 v[152:153], v152
	global_store_dwordx2 v[142:143], v[148:149], off
	v_lshlrev_b32_e32 v148, 16, v140
	v_and_b32_e32 v149, 0xffff0000, v140
	v_mul_f32_e32 v140, 0xbfb8aa3b, v148
	v_exp_f32_e32 v140, v140
	v_mul_f32_e32 v143, 0xbfb8aa3b, v149
	v_exp_f32_e32 v155, v143
	v_readlane_b32 s8, v145, 40
	v_add_f32_e32 v140, 1.0, v140
	v_rcp_f32_e32 v154, v140
	v_add_f32_e32 v140, 1.0, v155
	v_rcp_f32_e32 v155, v140
	s_waitcnt lgkmcnt(2)
	v_lshlrev_b32_e32 v142, 16, v146
	v_and_b32_e32 v143, 0xffff0000, v146
	v_readlane_b32 s64, v144, 40
	v_pk_add_f32 v[142:143], v[142:143], s[8:9] op_sel_hi:[1,0] neg_lo:[0,1] neg_hi:[0,1]
	v_pk_mul_f32 v[148:149], v[154:155], v[148:149]
	v_pk_mul_f32 v[142:143], s[64:65], v[142:143] op_sel_hi:[0,1]
	v_pk_fma_f32 v[142:143], v[128:129], v[142:143], v[132:133]
	v_lshlrev_b32_e32 v140, 16, v147
	v_pk_mul_f32 v[142:143], v[148:149], v[142:143]
	v_lshlrev_b32_e32 v148, 16, v141
	v_and_b32_e32 v149, 0xffff0000, v141
	v_mul_f32_e32 v141, 0xbfb8aa3b, v148
	v_exp_f32_e32 v146, v141
	v_mul_f32_e32 v141, 0xbfb8aa3b, v149
	v_exp_f32_e32 v154, v141
	v_and_b32_e32 v141, 0xffff0000, v147
	v_add_f32_e32 v146, 1.0, v146
	v_rcp_f32_e32 v146, v146
	v_add_f32_e32 v147, 1.0, v154
	v_rcp_f32_e32 v147, v147
	v_pk_add_f32 v[140:141], v[140:141], s[8:9] op_sel_hi:[1,0] neg_lo:[0,1] neg_hi:[0,1]
	s_add_u32 s8, s9, s36
	v_pk_mul_f32 v[140:141], s[64:65], v[140:141] op_sel_hi:[0,1]
	s_addc_u32 s65, s23, s37
	v_pk_fma_f32 v[140:141], v[130:131], v[140:141], v[134:135]
	v_pk_mul_f32 v[146:147], v[146:147], v[148:149]
	s_add_u32 s64, s8, s16
	v_pk_mul_f32 v[140:141], v[146:147], v[140:141]
	s_addc_u32 s65, s65, 0
	v_cvt_pk_bf16_f32 v142, v142, v143
	v_cvt_pk_bf16_f32 v143, v140, v141
	v_lshl_add_u64 v[140:141], s[64:65], 0, v[196:197]
	v_add_co_u32_e32 v140, vcc, s57, v140
	v_readlane_b32 s8, v145, 48
	s_nop 0
	v_addc_co_u32_e32 v141, vcc, 0, v141, vcc
	global_store_dwordx2 v[140:141], v[142:143], off
	v_lshlrev_b32_e32 v142, 16, v138
	v_and_b32_e32 v143, 0xffff0000, v138
	v_mul_f32_e32 v138, 0xbfb8aa3b, v142
	v_exp_f32_e32 v138, v138
	v_mul_f32_e32 v141, 0xbfb8aa3b, v143
	v_exp_f32_e32 v147, v141
	s_waitcnt lgkmcnt(1)
	v_lshlrev_b32_e32 v140, 16, v150
	v_add_f32_e32 v138, 1.0, v138
	v_rcp_f32_e32 v146, v138
	v_add_f32_e32 v138, 1.0, v147
	v_rcp_f32_e32 v147, v138
	v_and_b32_e32 v141, 0xffff0000, v150
	v_readlane_b32 s64, v144, 48
	v_pk_add_f32 v[140:141], v[140:141], s[8:9] op_sel_hi:[1,0] neg_lo:[0,1] neg_hi:[0,1]
	v_pk_mul_f32 v[142:143], v[146:147], v[142:143]
	v_pk_mul_f32 v[140:141], s[64:65], v[140:141] op_sel_hi:[0,1]
	v_pk_fma_f32 v[140:141], v[128:129], v[140:141], v[132:133]
	v_lshlrev_b32_e32 v138, 16, v151
	v_pk_mul_f32 v[140:141], v[142:143], v[140:141]
	v_lshlrev_b32_e32 v142, 16, v139
	v_and_b32_e32 v143, 0xffff0000, v139
	v_mul_f32_e32 v139, 0xbfb8aa3b, v142
	v_exp_f32_e32 v146, v139
	v_mul_f32_e32 v139, 0xbfb8aa3b, v143
	v_exp_f32_e32 v147, v139
	v_and_b32_e32 v139, 0xffff0000, v151
	v_add_f32_e32 v146, 1.0, v146
	v_rcp_f32_e32 v146, v146
	v_add_f32_e32 v147, 1.0, v147
	v_rcp_f32_e32 v147, v147
	v_pk_add_f32 v[138:139], v[138:139], s[8:9] op_sel_hi:[1,0] neg_lo:[0,1] neg_hi:[0,1]
	s_add_u32 s8, s9, s38
	v_pk_mul_f32 v[138:139], s[64:65], v[138:139] op_sel_hi:[0,1]
	s_addc_u32 s65, s23, s39
	v_pk_fma_f32 v[138:139], v[130:131], v[138:139], v[134:135]
	v_pk_mul_f32 v[142:143], v[146:147], v[142:143]
	s_add_u32 s64, s8, s16
	v_pk_mul_f32 v[138:139], v[142:143], v[138:139]
	s_addc_u32 s65, s65, 0
	v_cvt_pk_bf16_f32 v140, v140, v141
	v_cvt_pk_bf16_f32 v141, v138, v139
	v_lshl_add_u64 v[138:139], s[64:65], 0, v[196:197]
	v_add_co_u32_e32 v138, vcc, s57, v138
	v_readlane_b32 s8, v145, 56
	s_nop 0
	v_addc_co_u32_e32 v139, vcc, 0, v139, vcc
	global_store_dwordx2 v[138:139], v[140:141], off
	v_lshlrev_b32_e32 v140, 16, v136
	v_and_b32_e32 v141, 0xffff0000, v136
	v_mul_f32_e32 v136, 0xbfb8aa3b, v140
	v_exp_f32_e32 v136, v136
	v_mul_f32_e32 v139, 0xbfb8aa3b, v141
	v_exp_f32_e32 v143, v139
	s_waitcnt lgkmcnt(0)
; #define LAS __attribute__((address_space(3)))
; DI float bflo(unsigned w) { return __uint_as_float(w << 16); }
; DI float bfhi(unsigned w) { return __uint_as_float(w & 0xffff0000u); }
; DI unsigned pk2(float lo, float hi) { f32x2 v = {lo, hi}; bf16v2 b = __builtin_convertvector(v, bf16v2); return __builtin_bit_cast(unsigned, b); }
; DI float silu_f(float x) { return x * __builtin_amdgcn_rcpf(1.f + __expf(-x)); }
; #define MFMA32(a, b, c) __builtin_amdgcn_mfma_f32_32x32x16_bf16((a), (b), (c), 0, 0, 0)
; DI float bcast_lane(float v, int srclane) { return __uint_as_float(__builtin_amdgcn_readlane(__float_as_uint(v), srclane)); }
; #define RET_FRESH() int tid = tid0; asm volatile("" : "+v"(tid)); const int lane = tid & 63, r = lane & 31, h = lane >> 5; (void)r; (void)h; (void)tid
; DI void ret_unit(CParams& P, int l, int u, LAS unsigned char* lds, int tid_, int lane_, int wave_) {
;     ...
;         RET_FRESH();
; #pragma unroll
;         for (int dt = 0; dt < 8; ++dt) {
;             int ln = lane; asm volatile("" : "+v"(ln));
;             { const bf16x8 bS = pack_acc<0>(St[dt]);
; #pragma unroll
;               for (int ti = 0; ti < 2; ++ti) { const bf16x8 a = frag_row_perm(Qs, LD, 32 * ti, 32 * dt, ln); C[ti] = MFMA32(a, bS, C[ti]); } }
;             { const bf16x8 bS = pack_acc<1>(St[dt]);
; #pragma unroll
;               for (int ti = 0; ti < 2; ++ti) { const bf16x8 a = frag_row_perm(Qs, LD, 32 * ti, 32 * dt + 16, ln); C[ti] = MFMA32(a, bS, C[ti]); } }
;             asm volatile("" : "+v"(C[0]), "+v"(C[1]));
;         }
;     ...
; #pragma unroll
;         for (int i = 0; i < 8; ++i) { const float mean = bcast_lane(mean_l, 8 * i), rstd = bcast_lane(rstd_l, 8 * i);
;             const u32x2 w2 = *(const LAS u32x2*)(R + (wave * 8 + i) * LDR + 4 * lane); const float v0 = bflo(w2.x), v1 = bfhi(w2.x), v2 = bflo(w2.y), v3 = bfhi(w2.y);
;             const float g0 = bflo(gate[i].x), g1 = bfhi(gate[i].x), g2 = bflo(gate[i].y), g3 = bfhi(gate[i].y);
;             const float o0 = ((v0 - mean) * rstd * gn.x + gb.x) * silu_f(g0), o1 = ((v1 - mean) * rstd * gn.y + gb.y) * silu_f(g1);
;             const float o2 = ((v2 - mean) * rstd * gn.z + gb.z) * silu_f(g2), o3 = ((v3 - mean) * rstd * gn.w + gb.w) * silu_f(g3);
;             u32x2 w; w.x = pk2(o0, o1); w.y = pk2(o2, o3); *(u32x2*)(y + (size_t)(wave * 8 + i) * DM + 2048 + hh * 256 + 4 * lane) = w; }
	v_lshlrev_b32_e32 v138, 16, v152
	v_add_f32_e32 v136, 1.0, v136
	v_rcp_f32_e32 v142, v136
	v_add_f32_e32 v136, 1.0, v143
	v_rcp_f32_e32 v143, v136
	v_and_b32_e32 v139, 0xffff0000, v152
	v_readlane_b32 s64, v144, 56
	v_pk_add_f32 v[138:139], v[138:139], s[8:9] op_sel_hi:[1,0] neg_lo:[0,1] neg_hi:[0,1]
	v_lshlrev_b32_e32 v136, 16, v137
	v_pk_mul_f32 v[138:139], s[64:65], v[138:139] op_sel_hi:[0,1]
	v_pk_fma_f32 v[128:129], v[128:129], v[138:139], v[132:133]
	v_pk_mul_f32 v[132:133], v[142:143], v[140:141]
	v_and_b32_e32 v137, 0xffff0000, v137
	v_pk_mul_f32 v[128:129], v[132:133], v[128:129]
	v_mul_f32_e32 v133, 0xbfb8aa3b, v136
	v_exp_f32_e32 v138, v133
	v_mul_f32_e32 v133, 0xbfb8aa3b, v137
	v_exp_f32_e32 v139, v133
	v_lshlrev_b32_e32 v132, 16, v153
	v_add_f32_e32 v138, 1.0, v138
	v_rcp_f32_e32 v138, v138
	v_add_f32_e32 v139, 1.0, v139
	v_rcp_f32_e32 v139, v139
	v_and_b32_e32 v133, 0xffff0000, v153
	v_pk_add_f32 v[132:133], v[132:133], s[8:9] op_sel_hi:[1,0] neg_lo:[0,1] neg_hi:[0,1]
	s_add_u32 s8, s9, s40
	v_pk_mul_f32 v[132:133], s[64:65], v[132:133] op_sel_hi:[0,1]
	s_addc_u32 s9, s23, s41
	v_pk_fma_f32 v[130:131], v[130:131], v[132:133], v[134:135]
	v_pk_mul_f32 v[132:133], v[138:139], v[136:137]
	s_add_u32 s8, s8, s16
	v_pk_mul_f32 v[130:131], v[132:133], v[130:131]
	s_addc_u32 s9, s9, 0
	v_cvt_pk_bf16_f32 v128, v128, v129
	v_cvt_pk_bf16_f32 v129, v130, v131
	v_lshl_add_u64 v[130:131], s[8:9], 0, v[196:197]
	v_add_co_u32_e32 v130, vcc, s57, v130
	s_cmp_lg_u32 s22, 32
	s_nop 0
	v_addc_co_u32_e32 v131, vcc, 0, v131, vcc
	global_store_dwordx2 v[130:131], v[128:129], off
	s_cbranch_scc0 .LBB0_406
.LBB0_390:
	v_and_b32_e32 v160, 63, v180
	v_and_b32_e32 v161, 31, v160
	v_lshrrev_b32_e32 v160, 5, v160
	v_mul_u32_u24_e32 v161, 0x210, v161
	v_lshl_add_u32 v170, v160, 3, v161
	v_add_u32_e32 v171, 0x4000, v170
	s_mov_b32 s90, s22
	s_andn2_b64 vcc, exec, s[20:21]
	ds_read2_b64 v[198:201], v170 offset1:2
	ds_read2_b64 v[202:205], v171 offset0:64 offset1:66
	ds_read2_b64 v[206:209], v170 offset0:4 offset1:6
	v_cvt_pk_bf16_f32 v162, v0, v1
	v_cvt_pk_bf16_f32 v163, v2, v3
	v_cvt_pk_bf16_f32 v164, v4, v5
	v_cvt_pk_bf16_f32 v165, v6, v7
	ds_read2_b64 v[210:213], v171 offset0:68 offset1:70
	s_waitcnt lgkmcnt(3)
	v_mfma_f32_32x32x16_bf16 v[128:143], v[198:201], v[162:165], 0
	v_cvt_pk_bf16_f32 v166, v8, v9
	v_cvt_pk_bf16_f32 v167, v10, v11
	v_cvt_pk_bf16_f32 v168, v12, v13
	v_cvt_pk_bf16_f32 v169, v14, v15
	ds_read2_b64 v[198:201], v170 offset0:8 offset1:10
	s_waitcnt lgkmcnt(3)
	v_mfma_f32_32x32x16_bf16 v[144:159], v[202:205], v[162:165], 0
	ds_read2_b64 v[202:205], v171 offset0:72 offset1:74
	s_waitcnt lgkmcnt(3)
	v_mfma_f32_32x32x16_bf16 v[128:143], v[206:209], v[166:169], v[128:143]
	v_cvt_pk_bf16_f32 v162, v16, v17
	v_cvt_pk_bf16_f32 v163, v18, v19
	v_cvt_pk_bf16_f32 v164, v20, v21
	v_cvt_pk_bf16_f32 v165, v22, v23
	ds_read2_b64 v[206:209], v170 offset0:12 offset1:14
	s_waitcnt lgkmcnt(3)
	v_mfma_f32_32x32x16_bf16 v[144:159], v[210:213], v[166:169], v[144:159]
	ds_read2_b64 v[210:213], v171 offset0:76 offset1:78
	s_waitcnt lgkmcnt(3)
	v_mfma_f32_32x32x16_bf16 v[128:143], v[198:201], v[162:165], v[128:143]
	v_cvt_pk_bf16_f32 v166, v24, v25
	v_cvt_pk_bf16_f32 v167, v26, v27
	v_cvt_pk_bf16_f32 v168, v28, v29
	v_cvt_pk_bf16_f32 v169, v30, v31
	ds_read2_b64 v[198:201], v170 offset0:16 offset1:18
	s_waitcnt lgkmcnt(3)
	v_mfma_f32_32x32x16_bf16 v[144:159], v[202:205], v[162:165], v[144:159]
	ds_read2_b64 v[202:205], v171 offset0:80 offset1:82
	s_waitcnt lgkmcnt(3)
	v_mfma_f32_32x32x16_bf16 v[128:143], v[206:209], v[166:169], v[128:143]
	v_cvt_pk_bf16_f32 v162, v32, v33
	v_cvt_pk_bf16_f32 v163, v34, v35
	v_cvt_pk_bf16_f32 v164, v36, v37
	v_cvt_pk_bf16_f32 v165, v38, v39
	ds_read2_b64 v[206:209], v170 offset0:20 offset1:22
	s_waitcnt lgkmcnt(3)
	v_mfma_f32_32x32x16_bf16 v[144:159], v[210:213], v[166:169], v[144:159]
	ds_read2_b64 v[210:213], v171 offset0:84 offset1:86
	s_waitcnt lgkmcnt(3)
	v_mfma_f32_32x32x16_bf16 v[128:143], v[198:201], v[162:165], v[128:143]
	v_cvt_pk_bf16_f32 v166, v40, v41
	v_cvt_pk_bf16_f32 v167, v42, v43
	v_cvt_pk_bf16_f32 v168, v44, v45
	v_cvt_pk_bf16_f32 v169, v46, v47
	ds_read2_b64 v[198:201], v170 offset0:24 offset1:26
	s_waitcnt lgkmcnt(3)
	v_mfma_f32_32x32x16_bf16 v[144:159], v[202:205], v[162:165], v[144:159]
	ds_read2_b64 v[202:205], v171 offset0:88 offset1:90
	s_waitcnt lgkmcnt(3)
	v_mfma_f32_32x32x16_bf16 v[128:143], v[206:209], v[166:169], v[128:143]
	v_cvt_pk_bf16_f32 v162, v48, v49
	v_cvt_pk_bf16_f32 v163, v50, v51
	v_cvt_pk_bf16_f32 v164, v52, v53
	v_cvt_pk_bf16_f32 v165, v54, v55
	ds_read2_b64 v[206:209], v170 offset0:28 offset1:30
	s_waitcnt lgkmcnt(3)
	v_mfma_f32_32x32x16_bf16 v[144:159], v[210:213], v[166:169], v[144:159]
	ds_read2_b64 v[210:213], v171 offset0:92 offset1:94
	s_waitcnt lgkmcnt(3)
	v_mfma_f32_32x32x16_bf16 v[128:143], v[198:201], v[162:165], v[128:143]
	v_cvt_pk_bf16_f32 v166, v56, v57
	v_cvt_pk_bf16_f32 v167, v58, v59
	v_cvt_pk_bf16_f32 v168, v60, v61
	v_cvt_pk_bf16_f32 v169, v62, v63
	ds_read2_b64 v[198:201], v170 offset0:32 offset1:34
	s_waitcnt lgkmcnt(3)
	v_mfma_f32_32x32x16_bf16 v[144:159], v[202:205], v[162:165], v[144:159]
	ds_read2_b64 v[202:205], v171 offset0:96 offset1:98
	s_waitcnt lgkmcnt(3)
	v_mfma_f32_32x32x16_bf16 v[128:143], v[206:209], v[166:169], v[128:143]
	v_cvt_pk_bf16_f32 v162, v64, v65
	v_cvt_pk_bf16_f32 v163, v66, v67
	v_cvt_pk_bf16_f32 v164, v68, v69
	v_cvt_pk_bf16_f32 v165, v70, v71
	ds_read2_b64 v[206:209], v170 offset0:36 offset1:38
	s_waitcnt lgkmcnt(3)
	v_mfma_f32_32x32x16_bf16 v[144:159], v[210:213], v[166:169], v[144:159]
	ds_read2_b64 v[210:213], v171 offset0:100 offset1:102
	s_waitcnt lgkmcnt(3)
; #define MFMA32(a, b, c) __builtin_amdgcn_mfma_f32_32x32x16_bf16((a), (b), (c), 0, 0, 0)
; #define RET_FRESH() int tid = tid0; asm volatile("" : "+v"(tid)); const int lane = tid & 63, r = lane & 31, h = lane >> 5; (void)r; (void)h; (void)tid
; #define RET_VMWAIT() asm volatile("s_waitcnt vmcnt(0)" ::: "memory")
; #define wave (__builtin_amdgcn_readfirstlane(tid >> 6))
; DI void ret_unit(CParams& P, int l, int u, LAS unsigned char* lds, int tid_, int lane_, int wave_) {
;     ...
;         RET_FRESH();
; #pragma unroll
;         for (int dt = 0; dt < 8; ++dt) {
;             int ln = lane; asm volatile("" : "+v"(ln));
;             { const bf16x8 bS = pack_acc<0>(St[dt]);
; #pragma unroll
;               for (int ti = 0; ti < 2; ++ti) { const bf16x8 a = frag_row_perm(Qs, LD, 32 * ti, 32 * dt, ln); C[ti] = MFMA32(a, bS, C[ti]); } }
;             { const bf16x8 bS = pack_acc<1>(St[dt]);
; #pragma unroll
;               for (int ti = 0; ti < 2; ++ti) { const bf16x8 a = frag_row_perm(Qs, LD, 32 * ti, 32 * dt + 16, ln); C[ti] = MFMA32(a, bS, C[ti]); } }
;             asm volatile("" : "+v"(C[0]), "+v"(C[1]));
;         }
; #pragma unroll
;         for (int ti = 0; ti < 2; ++ti)
; #pragma unroll
;             for (int i = 0; i < 16; ++i) C[ti][i] *= g64;
;         }
;         RET_VMWAIT();
;         __syncthreads();
;         if (wave < 4) { RET_FRESH(); const int ti = wave >> 1, si = wave & 1;
;           f32x16 acc = zero16();
;           if (si <= ti) {
; #pragma unroll
;               for (int ks = 0; ks < 16; ++ks) { const bf16x8 a = frag_row(Qs, LD, 32 * ti, 16 * ks, lane), bb = frag_row(Ks, LD, 32 * si, 16 * ks, lane); acc = MFMA32(a, bb, acc); } }
	v_mfma_f32_32x32x16_bf16 v[128:143], v[198:201], v[162:165], v[128:143]
	v_cvt_pk_bf16_f32 v166, v72, v73
	v_cvt_pk_bf16_f32 v167, v74, v75
	v_cvt_pk_bf16_f32 v168, v76, v77
	v_cvt_pk_bf16_f32 v169, v78, v79
	ds_read2_b64 v[198:201], v170 offset0:40 offset1:42
	s_waitcnt lgkmcnt(3)
	v_mfma_f32_32x32x16_bf16 v[144:159], v[202:205], v[162:165], v[144:159]
	ds_read2_b64 v[202:205], v171 offset0:104 offset1:106
	s_waitcnt lgkmcnt(3)
	v_mfma_f32_32x32x16_bf16 v[128:143], v[206:209], v[166:169], v[128:143]
	v_cvt_pk_bf16_f32 v162, v80, v81
	v_cvt_pk_bf16_f32 v163, v82, v83
	v_cvt_pk_bf16_f32 v164, v84, v85
	v_cvt_pk_bf16_f32 v165, v86, v87
	ds_read2_b64 v[206:209], v170 offset0:44 offset1:46
	s_waitcnt lgkmcnt(3)
	v_mfma_f32_32x32x16_bf16 v[144:159], v[210:213], v[166:169], v[144:159]
	ds_read2_b64 v[210:213], v171 offset0:108 offset1:110
	s_waitcnt lgkmcnt(3)
	v_mfma_f32_32x32x16_bf16 v[128:143], v[198:201], v[162:165], v[128:143]
	v_cvt_pk_bf16_f32 v166, v88, v89
	v_cvt_pk_bf16_f32 v167, v90, v91
	v_cvt_pk_bf16_f32 v168, v92, v93
	v_cvt_pk_bf16_f32 v169, v94, v95
	ds_read2_b64 v[198:201], v170 offset0:48 offset1:50
	s_waitcnt lgkmcnt(3)
	v_mfma_f32_32x32x16_bf16 v[144:159], v[202:205], v[162:165], v[144:159]
	ds_read2_b64 v[202:205], v171 offset0:112 offset1:114
	s_waitcnt lgkmcnt(3)
	v_mfma_f32_32x32x16_bf16 v[128:143], v[206:209], v[166:169], v[128:143]
	v_cvt_pk_bf16_f32 v162, v96, v97
	v_cvt_pk_bf16_f32 v163, v98, v99
	v_cvt_pk_bf16_f32 v164, v100, v101
	v_cvt_pk_bf16_f32 v165, v102, v103
	ds_read2_b64 v[206:209], v170 offset0:52 offset1:54
	s_waitcnt lgkmcnt(3)
	v_mfma_f32_32x32x16_bf16 v[144:159], v[210:213], v[166:169], v[144:159]
	ds_read2_b64 v[210:213], v171 offset0:116 offset1:118
	s_waitcnt lgkmcnt(3)
	v_mfma_f32_32x32x16_bf16 v[128:143], v[198:201], v[162:165], v[128:143]
	v_cvt_pk_bf16_f32 v166, v104, v105
	v_cvt_pk_bf16_f32 v167, v106, v107
	v_cvt_pk_bf16_f32 v168, v108, v109
	v_cvt_pk_bf16_f32 v169, v110, v111
	ds_read2_b64 v[198:201], v170 offset0:56 offset1:58
	s_waitcnt lgkmcnt(3)
	v_mfma_f32_32x32x16_bf16 v[144:159], v[202:205], v[162:165], v[144:159]
	ds_read2_b64 v[202:205], v171 offset0:120 offset1:122
	s_waitcnt lgkmcnt(3)
	v_mfma_f32_32x32x16_bf16 v[128:143], v[206:209], v[166:169], v[128:143]
	v_cvt_pk_bf16_f32 v162, v112, v113
	v_cvt_pk_bf16_f32 v163, v114, v115
	v_cvt_pk_bf16_f32 v164, v116, v117
	v_cvt_pk_bf16_f32 v165, v118, v119
	ds_read2_b64 v[206:209], v170 offset0:60 offset1:62
	s_waitcnt lgkmcnt(3)
	v_mfma_f32_32x32x16_bf16 v[144:159], v[210:213], v[166:169], v[144:159]
	ds_read2_b64 v[210:213], v171 offset0:124 offset1:126
	s_waitcnt lgkmcnt(3)
	v_mfma_f32_32x32x16_bf16 v[128:143], v[198:201], v[162:165], v[128:143]
	v_cvt_pk_bf16_f32 v166, v120, v121
	v_cvt_pk_bf16_f32 v167, v122, v123
	v_cvt_pk_bf16_f32 v168, v124, v125
	v_cvt_pk_bf16_f32 v169, v126, v127
	s_waitcnt lgkmcnt(2)
	v_mfma_f32_32x32x16_bf16 v[144:159], v[202:205], v[162:165], v[144:159]
	s_waitcnt lgkmcnt(1)
	v_mfma_f32_32x32x16_bf16 v[128:143], v[206:209], v[166:169], v[128:143]
	s_waitcnt lgkmcnt(0)
	v_mfma_f32_32x32x16_bf16 v[144:159], v[210:213], v[166:169], v[144:159]
	s_nop 1
	s_waitcnt vmcnt(0)
	s_barrier
	s_cbranch_vccnz .LBB0_396
	v_mov_b32_e32 v177, v180
	v_readlane_b32 s22, v255, 40
	v_readlane_b32 s23, v255, 41
	v_and_b32_e32 v160, 31, v177
	s_mov_b64 s[8:9], -1
	s_and_b64 vcc, exec, s[22:23]
	v_or_b32_e32 v178, s96, v160
	s_cbranch_vccz .LBB0_393
	v_or_b32_e32 v161, s91, v160
	v_lshrrev_b32_e32 v162, 1, v177
	v_mul_lo_u32 v161, v161, s93
	v_and_b32_e32 v166, 16, v162
	v_add3_u32 v179, 0, v161, v166
	ds_read_b128 v[162:165], v179
	v_or_b32_e32 v176, s96, v160
	v_mul_u32_u24_e32 v160, 0x210, v176
	v_add3_u32 v181, 0, v160, v166
	ds_read_b128 v[166:169], v181 offset:33792
	ds_read_b128 v[182:185], v179 offset:32
	ds_read_b128 v[186:189], v181 offset:33824
	s_mov_b64 s[8:9], 0
	s_waitcnt lgkmcnt(2)
	v_mfma_f32_32x32x16_bf16 v[160:175], v[162:165], v[166:169], 0
	s_waitcnt lgkmcnt(0)
	v_mfma_f32_32x32x16_bf16 v[160:175], v[182:185], v[186:189], v[160:175]
	ds_read_b128 v[182:185], v179 offset:64
	ds_read_b128 v[186:189], v181 offset:33856
	s_waitcnt lgkmcnt(0)
	v_mfma_f32_32x32x16_bf16 v[160:175], v[182:185], v[186:189], v[160:175]
	ds_read_b128 v[182:185], v179 offset:96
	ds_read_b128 v[186:189], v181 offset:33888
	s_waitcnt lgkmcnt(0)
	v_mfma_f32_32x32x16_bf16 v[160:175], v[182:185], v[186:189], v[160:175]
	ds_read_b128 v[182:185], v179 offset:128
	ds_read_b128 v[186:189], v181 offset:33920
	s_waitcnt lgkmcnt(0)
	v_mfma_f32_32x32x16_bf16 v[160:175], v[182:185], v[186:189], v[160:175]
	ds_read_b128 v[182:185], v179 offset:160
	ds_read_b128 v[186:189], v181 offset:33952
	s_waitcnt lgkmcnt(0)
	v_mfma_f32_32x32x16_bf16 v[160:175], v[182:185], v[186:189], v[160:175]
	ds_read_b128 v[182:185], v179 offset:192
	ds_read_b128 v[186:189], v181 offset:33984
	s_waitcnt lgkmcnt(0)
	v_mfma_f32_32x32x16_bf16 v[160:175], v[182:185], v[186:189], v[160:175]
	ds_read_b128 v[182:185], v179 offset:224
	ds_read_b128 v[186:189], v181 offset:34016
	s_waitcnt lgkmcnt(0)
	v_mfma_f32_32x32x16_bf16 v[160:175], v[182:185], v[186:189], v[160:175]
	ds_read_b128 v[182:185], v179 offset:256
	ds_read_b128 v[186:189], v181 offset:34048
	s_waitcnt lgkmcnt(0)
	v_mfma_f32_32x32x16_bf16 v[160:175], v[182:185], v[186:189], v[160:175]
	ds_read_b128 v[182:185], v179 offset:288
	ds_read_b128 v[186:189], v181 offset:34080
	s_waitcnt lgkmcnt(0)
	v_mfma_f32_32x32x16_bf16 v[160:175], v[182:185], v[186:189], v[160:175]
	ds_read_b128 v[182:185], v179 offset:320
	ds_read_b128 v[186:189], v181 offset:34112
	s_waitcnt lgkmcnt(0)
	v_mfma_f32_32x32x16_bf16 v[160:175], v[182:185], v[186:189], v[160:175]
	ds_read_b128 v[182:185], v179 offset:352
	ds_read_b128 v[186:189], v181 offset:34144
	s_waitcnt lgkmcnt(0)
	v_mfma_f32_32x32x16_bf16 v[160:175], v[182:185], v[186:189], v[160:175]
	ds_read_b128 v[182:185], v179 offset:384
	ds_read_b128 v[186:189], v181 offset:34176
	s_waitcnt lgkmcnt(0)
	v_mfma_f32_32x32x16_bf16 v[160:175], v[182:185], v[186:189], v[160:175]
	ds_read_b128 v[182:185], v179 offset:416
	ds_read_b128 v[186:189], v181 offset:34208
	s_waitcnt lgkmcnt(0)
	v_mfma_f32_32x32x16_bf16 v[160:175], v[182:185], v[186:189], v[160:175]
	ds_read_b128 v[182:185], v179 offset:448
	ds_read_b128 v[186:189], v181 offset:34240
	s_waitcnt lgkmcnt(0)
	v_mfma_f32_32x32x16_bf16 v[160:175], v[182:185], v[186:189], v[160:175]
	ds_read_b128 v[182:185], v179 offset:480
	ds_read_b128 v[186:189], v181 offset:34272
	s_waitcnt lgkmcnt(0)
	v_mfma_f32_32x32x16_bf16 v[160:175], v[182:185], v[186:189], v[160:175]

; DI unsigned f2bf(float f) { unsigned u = __float_as_uint(f); return (u + 0x7fffu + ((u >> 16) & 1u)) >> 16; }
; DI int crow(int reg, int h) { return (reg & 3) + 8 * (reg >> 2) + 4 * h; }
; #define MFMA32(a, b, c) __builtin_amdgcn_mfma_f32_32x32x16_bf16((a), (b), (c), 0, 0, 0)
; #define RET_FRESH() int tid = tid0; asm volatile("" : "+v"(tid)); const int lane = tid & 63, r = lane & 31, h = lane >> 5; (void)r; (void)h; (void)tid
; #define RET_VMWAIT() asm volatile("s_waitcnt vmcnt(0)" ::: "memory")
; #define wave (__builtin_amdgcn_readfirstlane(tid >> 6))
; DI void ret_unit(CParams& P, int l, int u, LAS unsigned char* lds, int tid_, int lane_, int wave_) {
;     ...
;         for (int ti = 0; ti < 2; ++ti)
; #pragma unroll
;             for (int i = 0; i < 16; ++i) C[ti][i] *= g64;
;         }
;         RET_VMWAIT();
;         __syncthreads();
;         if (wave < 4) { RET_FRESH(); const int ti = wave >> 1, si = wave & 1;
;           f32x16 acc = zero16();
;           if (si <= ti) {
; #pragma unroll
;               for (int ks = 0; ks < 16; ++ks) { const bf16x8 a = frag_row(Qs, LD, 32 * ti, 16 * ks, lane), bb = frag_row(Ks, LD, 32 * si, 16 * ks, lane); acc = MFMA32(a, bb, acc); } }
; #pragma unroll
;           for (int i = 0; i < 16; ++i) { const int t = 32 * ti + crow(i, h), s = 32 * si + r; float v = acc[i]; if (s > t) v = 0.f; Ps[t * LDP + s] = (bf16_t)f2bf(v); } }
;         __syncthreads();
;         {
;         RET_FRESH();
;         if (n + 1 < 32) RET_DMA(0, n + 1);
;         bf16x8 bv[4];
; #pragma unroll
;         for (int ks = 0; ks < 4; ++ks) { bv[ks] = frag_tr(Vs, LD, 16 * ks, 32 * wave, lane);
; #pragma unroll
;             for (int ti = 0; ti < 2; ++ti) { const bf16x8 a = frag_row(Ps, LDP, 32 * ti, 16 * ks, lane); C[ti] = MFMA32(a, bv[ks], C[ti]); } }
; #pragma unroll
;         for (int ti = 0; ti < 2; ++ti)
; #pragma unroll
;             for (int i = 0; i < 16; ++i) R[(32 * ti + crow(i, h)) * LDR + 32 * wave + r] = (bf16_t)f2bf(C[ti][i]);
.LBB0_400:
	v_lshrrev_b32_e32 v161, 2, v182
	v_and_b32_e32 v183, 31, v182
	v_and_b32_e32 v160, 16, v182
	v_lshlrev_b32_e32 v196, 3, v181
	v_lshrrev_b32_e32 v163, 1, v182
	v_and_b32_e32 v161, 11, v161
	v_lshl_add_u32 v160, v160, 1, s83
	v_and_b32_e32 v162, 24, v196
	v_and_b32_e32 v163, 16, v163
	v_mul_u32_u24_e32 v164, 0x90, v183
	v_mul_u32_u24_e32 v161, 0x210, v161
	v_readlane_b32 s23, v255, 9
	v_add3_u32 v188, v160, v162, v161
	ds_read_b64_tr_b16 v[176:177], v188
	ds_read_b64_tr_b16 v[178:179], v188 offset:2112
	v_add3_u32 v189, s23, v163, v164
	ds_read_b128 v[184:187], v189
	v_mov_b32_e32 v193, v192
	v_pk_mul_f32 v[174:175], v[192:193], v[142:143]
	v_pk_mul_f32 v[172:173], v[192:193], v[140:141]
	v_pk_mul_f32 v[170:171], v[192:193], v[138:139]
	v_pk_mul_f32 v[168:169], v[192:193], v[136:137]
	v_pk_mul_f32 v[166:167], v[192:193], v[134:135]
	v_pk_mul_f32 v[164:165], v[192:193], v[132:133]
	v_pk_mul_f32 v[162:163], v[192:193], v[130:131]
	v_pk_mul_f32 v[160:161], v[194:195], v[128:129]
	v_pk_mul_f32 v[134:135], v[192:193], v[150:151]
	v_pk_mul_f32 v[132:133], v[192:193], v[148:149]
	s_waitcnt lgkmcnt(0)
	v_mfma_f32_32x32x16_bf16 v[160:175], v[184:187], v[176:179], v[160:175]
	ds_read_b128 v[184:187], v189 offset:4608
	v_mul_f32_e64 v130, v192, v146
	v_mul_f32_e64 v131, v193, v147
	v_mul_f32_e64 v128, v194, v144
	v_mul_f32_e64 v129, v195, v145
	ds_read_b128 v[148:151], v189 offset:32
	ds_read_b64_tr_b16 v[144:145], v188 offset:8448
	ds_read_b64_tr_b16 v[146:147], v188 offset:10560
	v_pk_mul_f32 v[142:143], v[192:193], v[158:159]
	v_pk_mul_f32 v[140:141], v[192:193], v[156:157]
	v_pk_mul_f32 v[138:139], v[192:193], v[154:155]
	v_pk_mul_f32 v[136:137], v[192:193], v[152:153]
	s_waitcnt lgkmcnt(0)
	v_mfma_f32_32x32x16_bf16 v[160:175], v[148:151], v[144:147], v[160:175]
	ds_read_b128 v[148:151], v189 offset:4640
	s_lshl_b32 s23, s90, 6
	v_readlane_b32 s64, v254, 11
	s_add_i32 s64, s23, s64
	s_ashr_i32 s65, s64, 31
	s_mul_i32 s23, s64, 0x6000
	s_mul_hi_i32 s88, s64, 0x6000
	v_mfma_f32_32x32x16_bf16 v[128:143], v[184:187], v[176:179], v[128:143]
	s_add_u32 s23, s14, s23
	s_addc_u32 s90, s15, s88
	s_add_u32 s88, s23, s80
	s_addc_u32 s89, s90, s69
	s_add_u32 s88, s88, s16
	s_addc_u32 s89, s89, 0
	s_mov_b32 s57, 0x1a204000
	s_waitcnt lgkmcnt(0)
	v_mfma_f32_32x32x16_bf16 v[128:143], v[148:151], v[144:147], v[128:143]
	ds_read_b128 v[152:155], v189 offset:64
	ds_read_b64_tr_b16 v[148:149], v188 offset:16896
	ds_read_b64_tr_b16 v[150:151], v188 offset:19008
	v_mul_f32_e64 v14, v192, v14
	v_mul_f32_e64 v15, v193, v15
	v_pk_mul_f32 v[12:13], v[192:193], v[12:13]
	v_pk_mul_f32 v[10:11], v[192:193], v[10:11]
	v_pk_mul_f32 v[8:9], v[192:193], v[8:9]
	v_pk_mul_f32 v[6:7], v[192:193], v[6:7]
	v_pk_mul_f32 v[4:5], v[192:193], v[4:5]
	s_waitcnt lgkmcnt(0)
	v_mfma_f32_32x32x16_bf16 v[160:175], v[152:155], v[148:151], v[160:175]
	ds_read_b128 v[152:155], v189 offset:4672
	v_mul_f32_e64 v2, v192, v2
	v_mul_f32_e64 v3, v193, v3
	v_mul_f32_e64 v0, v194, v0
	v_mul_f32_e64 v1, v195, v1
	v_pk_mul_f32 v[30:31], v[192:193], v[30:31]
	v_pk_mul_f32 v[28:29], v[192:193], v[28:29]
	v_pk_mul_f32 v[26:27], v[192:193], v[26:27]
	v_pk_mul_f32 v[24:25], v[192:193], v[24:25]
	s_waitcnt lgkmcnt(0)
	v_mfma_f32_32x32x16_bf16 v[128:143], v[152:155], v[148:151], v[128:143]
	ds_read_b128 v[156:159], v189 offset:96
	ds_read_b64_tr_b16 v[152:153], v188 offset:25344
	ds_read_b64_tr_b16 v[154:155], v188 offset:27456
	ds_read_b128 v[184:187], v189 offset:4704
	v_mul_f32_e64 v22, v192, v22
	v_mul_f32_e64 v23, v193, v23
	v_pk_mul_f32 v[20:21], v[192:193], v[20:21]
	v_pk_mul_f32 v[18:19], v[192:193], v[18:19]
	v_pk_mul_f32 v[16:17], v[194:195], v[16:17]
	v_pk_mul_f32 v[46:47], v[192:193], v[46:47]
	s_waitcnt lgkmcnt(1)
	v_mfma_f32_32x32x16_bf16 v[160:175], v[156:159], v[152:155], v[160:175]
	v_lshlrev_b32_e32 v158, 6, v182
	v_lshlrev_b32_e32 v156, 1, v183
	v_and_b32_e32 v158, 0x800, v158
	v_add3_u32 v156, s92, v156, v158
	v_mul_f32_e64 v44, v192, v44
	v_mul_f32_e64 v45, v193, v45
	v_pk_mul_f32 v[42:43], v[192:193], v[42:43]
	v_pk_mul_f32 v[40:41], v[192:193], v[40:41]
	s_nop 3
	v_bfe_u32 v157, v160, 16, 1
	v_add3_u32 v157, v160, v157, s79
	ds_write_b16_d16_hi v156, v157
	v_bfe_u32 v157, v161, 16, 1
	v_add3_u32 v157, v161, v157, s79
	ds_write_b16_d16_hi v156, v157 offset:512
	v_bfe_u32 v157, v162, 16, 1
	v_add3_u32 v157, v162, v157, s79
	ds_write_b16_d16_hi v156, v157 offset:1024
	v_bfe_u32 v157, v163, 16, 1
	v_add3_u32 v157, v163, v157, s79
	ds_write_b16_d16_hi v156, v157 offset:1536
	v_bfe_u32 v157, v164, 16, 1
	v_add3_u32 v157, v164, v157, s79
	ds_write_b16_d16_hi v156, v157 offset:4096
	v_bfe_u32 v157, v165, 16, 1
	v_add3_u32 v157, v165, v157, s79
	ds_write_b16_d16_hi v156, v157 offset:4608
	v_bfe_u32 v157, v166, 16, 1
	v_add3_u32 v157, v166, v157, s79
	ds_write_b16_d16_hi v156, v157 offset:5120
	v_bfe_u32 v157, v167, 16, 1
	v_add3_u32 v157, v167, v157, s79
	ds_write_b16_d16_hi v156, v157 offset:5632
	v_bfe_u32 v157, v168, 16, 1
	v_add3_u32 v157, v168, v157, s79
	ds_write_b16_d16_hi v156, v157 offset:8192
	v_bfe_u32 v157, v169, 16, 1
	v_add3_u32 v157, v169, v157, s79
	ds_write_b16_d16_hi v156, v157 offset:8704
	v_bfe_u32 v157, v170, 16, 1
	v_add3_u32 v157, v170, v157, s79
	ds_write_b16_d16_hi v156, v157 offset:9216
	v_bfe_u32 v157, v171, 16, 1
	v_add3_u32 v157, v171, v157, s79
	s_waitcnt lgkmcnt(11)
; DI unsigned f2bf(float f) { unsigned u = __float_as_uint(f); return (u + 0x7fffu + ((u >> 16) & 1u)) >> 16; }
; DI int crow(int reg, int h) { return (reg & 3) + 8 * (reg >> 2) + 4 * h; }
; #define MFMA32(a, b, c) __builtin_amdgcn_mfma_f32_32x32x16_bf16((a), (b), (c), 0, 0, 0)
; #define wave (__builtin_amdgcn_readfirstlane(tid >> 6))
; DI void ret_unit(CParams& P, int l, int u, LAS unsigned char* lds, int tid_, int lane_, int wave_) {
;     ...
;             for (int i = 0; i < 16; ++i) R[(32 * ti + crow(i, h)) * LDR + 32 * wave + r] = (bf16_t)f2bf(C[ti][i]);
;         asm volatile("" ::: "memory");
; #pragma unroll
;         for (int i = 0; i < 8; ++i) gate[i] = *(const u32x2*)(proj + (size_t)(wave * 8 + i) * NPROJ + C_CG + hh * 256 + 4 * lane);
; #pragma unroll
;         for (int dt = 0; dt < 8; ++dt) {
;             int ln = lane; asm volatile("" : "+v"(ln));
; #pragma unroll
;             for (int i = 0; i < 16; ++i) St[dt][i] *= g64;
; #pragma unroll
;             for (int ks = 0; ks < 4; ++ks) { const bf16x8 a = frag_tr(Ks, LD, 16 * ks, 32 * dt, ln); St[dt] = MFMA32(a, bv[ks], St[dt]); }
	v_mfma_f32_32x32x16_bf16 v[128:143], v[184:187], v[152:155], v[128:143]
	ds_write_b16_d16_hi v156, v157 offset:9728
	v_bfe_u32 v157, v172, 16, 1
	v_add3_u32 v157, v172, v157, s79
	ds_write_b16_d16_hi v156, v157 offset:12288
	v_bfe_u32 v157, v173, 16, 1
	v_add3_u32 v157, v173, v157, s79
	ds_write_b16_d16_hi v156, v157 offset:12800
	v_bfe_u32 v157, v174, 16, 1
	v_add3_u32 v157, v174, v157, s79
	ds_write_b16_d16_hi v156, v157 offset:13312
	v_bfe_u32 v157, v175, 16, 1
	v_add3_u32 v157, v175, v157, s79
	ds_write_b16_d16_hi v156, v157 offset:13824
	v_bfe_u32 v157, v128, 16, 1
	v_add3_u32 v128, v128, v157, s79
	ds_write_b16_d16_hi v156, v128 offset:16384
	v_bfe_u32 v128, v129, 16, 1
	v_add3_u32 v128, v129, v128, s79
	ds_write_b16_d16_hi v156, v128 offset:16896
	v_bfe_u32 v128, v130, 16, 1
	v_add3_u32 v128, v130, v128, s79
	ds_write_b16_d16_hi v156, v128 offset:17408
	v_bfe_u32 v128, v131, 16, 1
	v_add3_u32 v128, v131, v128, s79
	ds_write_b16_d16_hi v156, v128 offset:17920
	v_bfe_u32 v128, v132, 16, 1
	v_add3_u32 v128, v132, v128, s79
	ds_write_b16_d16_hi v156, v128 offset:20480
	v_bfe_u32 v128, v133, 16, 1
	v_add3_u32 v128, v133, v128, s79
	ds_write_b16_d16_hi v156, v128 offset:20992
	v_bfe_u32 v128, v134, 16, 1
	v_add3_u32 v128, v134, v128, s79
	ds_write_b16_d16_hi v156, v128 offset:21504
	v_bfe_u32 v128, v135, 16, 1
	v_add3_u32 v128, v135, v128, s79
	ds_write_b16_d16_hi v156, v128 offset:22016
	v_bfe_u32 v128, v136, 16, 1
	v_add3_u32 v128, v136, v128, s79
	ds_write_b16_d16_hi v156, v128 offset:24576
	v_bfe_u32 v128, v137, 16, 1
	v_add3_u32 v128, v137, v128, s79
	ds_write_b16_d16_hi v156, v128 offset:25088
	v_bfe_u32 v128, v138, 16, 1
	v_add3_u32 v128, v138, v128, s79
	ds_write_b16_d16_hi v156, v128 offset:25600
	v_bfe_u32 v128, v139, 16, 1
	v_add3_u32 v128, v139, v128, s79
	ds_write_b16_d16_hi v156, v128 offset:26112
	v_bfe_u32 v128, v140, 16, 1
	v_add3_u32 v128, v140, v128, s79
	ds_write_b16_d16_hi v156, v128 offset:28672
	v_bfe_u32 v128, v141, 16, 1
	v_add3_u32 v128, v141, v128, s79
	ds_write_b16_d16_hi v156, v128 offset:29184
	v_bfe_u32 v128, v142, 16, 1
	v_add3_u32 v128, v142, v128, s79
	ds_write_b16_d16_hi v156, v128 offset:29696
	v_bfe_u32 v128, v143, 16, 1
	v_add3_u32 v128, v143, v128, s79
	ds_write_b16_d16_hi v156, v128 offset:30208
	v_lshl_add_u64 v[128:129], s[88:89], 0, v[196:197]
	s_add_u32 s88, s23, s73
	s_addc_u32 s89, s90, s3
	v_add_co_u32_e32 v128, vcc, s57, v128
	s_add_u32 s88, s88, s16
	s_nop 0
	v_addc_co_u32_e32 v129, vcc, 0, v129, vcc
	s_addc_u32 s89, s89, 0
	global_load_dwordx2 v[162:163], v[128:129], off offset:2048
	v_lshl_add_u64 v[128:129], s[88:89], 0, v[196:197]
	s_add_u32 s88, s23, s75
	s_addc_u32 s89, s90, s74
	v_add_co_u32_e32 v128, vcc, s57, v128
	s_add_u32 s88, s88, s16
	s_nop 0
	v_addc_co_u32_e32 v129, vcc, 0, v129, vcc
	s_addc_u32 s89, s89, 0
	global_load_dwordx2 v[160:161], v[128:129], off offset:2048
	v_lshl_add_u64 v[128:129], s[88:89], 0, v[196:197]
	s_add_u32 s88, s23, s78
	s_addc_u32 s89, s90, s47
	v_add_co_u32_e32 v128, vcc, s57, v128
	s_add_u32 s88, s88, s16
	s_nop 0
	v_addc_co_u32_e32 v129, vcc, 0, v129, vcc
	s_addc_u32 s89, s89, 0
	global_load_dwordx2 v[158:159], v[128:129], off offset:2048
	v_lshl_add_u64 v[128:129], s[88:89], 0, v[196:197]
	s_add_u32 s88, s23, s72
	s_addc_u32 s89, s90, s54
	v_add_co_u32_e32 v128, vcc, s57, v128
	s_add_u32 s88, s88, s16
	s_nop 0
	v_addc_co_u32_e32 v129, vcc, 0, v129, vcc
	s_addc_u32 s89, s89, 0
	global_load_dwordx2 v[156:157], v[128:129], off offset:2048
	v_lshl_add_u64 v[128:129], s[88:89], 0, v[196:197]
	s_add_u32 s88, s23, s0
	s_addc_u32 s89, s90, s1
	v_add_co_u32_e32 v128, vcc, s57, v128
	s_add_u32 s88, s88, s16
	s_nop 0
	v_addc_co_u32_e32 v129, vcc, 0, v129, vcc
	s_addc_u32 s89, s89, 0
	global_load_dwordx2 v[142:143], v[128:129], off offset:2048
	v_lshl_add_u64 v[128:129], s[88:89], 0, v[196:197]
	s_add_u32 s88, s23, s63
	s_addc_u32 s89, s90, s62
	v_add_co_u32_e32 v128, vcc, s57, v128
	s_add_u32 s88, s88, s16
	s_nop 0
	v_addc_co_u32_e32 v129, vcc, 0, v129, vcc
	s_addc_u32 s89, s89, 0
	global_load_dwordx2 v[140:141], v[128:129], off offset:2048
	v_lshl_add_u64 v[128:129], s[88:89], 0, v[196:197]
	s_add_u32 s88, s23, s44
	s_addc_u32 s89, s90, s46
	v_add_co_u32_e32 v128, vcc, s57, v128
	s_add_u32 s88, s88, s16
	s_nop 0
	v_addc_co_u32_e32 v129, vcc, 0, v129, vcc
	s_addc_u32 s89, s89, 0
	global_load_dwordx2 v[138:139], v[128:129], off offset:2048
	v_lshl_add_u64 v[128:129], s[88:89], 0, v[196:197]
	v_add_co_u32_e32 v128, vcc, s57, v128
	v_pk_mul_f32 v[38:39], v[192:193], v[38:39]
	s_nop 0
	v_addc_co_u32_e32 v129, vcc, 0, v129, vcc
	global_load_dwordx2 v[136:137], v[128:129], off offset:2048
	v_mov_b32_e32 v128, v181
	v_pk_mul_f32 v[36:37], v[192:193], v[36:37]
	v_lshrrev_b32_e32 v130, 2, v128
	v_and_b32_e32 v129, 16, v128
	v_and_b32_e32 v130, 0xffffffb, v130
	v_lshlrev_b32_e32 v128, 3, v128
	v_lshl_add_u32 v129, v129, 1, 0
	v_and_b32_e32 v128, 24, v128
	v_mul_lo_u32 v130, v130, s93
	v_add3_u32 v132, v129, v128, v130
	ds_read_b64_tr_b16 v[128:129], v132 offset:33792
	ds_read_b64_tr_b16 v[130:131], v132 offset:35904
	s_waitcnt lgkmcnt(0)
	v_mfma_f32_32x32x16_bf16 v[0:15], v[128:131], v[176:179], v[0:15]
	ds_read_b64_tr_b16 v[128:129], v132 offset:42240
	ds_read_b64_tr_b16 v[130:131], v132 offset:44352
	v_mul_f32_e64 v34, v192, v34
	v_mul_f32_e64 v35, v193, v35
	v_mul_f32_e64 v32, v194, v32
	v_mul_f32_e64 v33, v195, v33
	v_pk_mul_f32 v[62:63], v[192:193], v[62:63]
	v_pk_mul_f32 v[60:61], v[192:193], v[60:61]
	v_pk_mul_f32 v[58:59], v[192:193], v[58:59]
	v_pk_mul_f32 v[56:57], v[192:193], v[56:57]
	s_waitcnt lgkmcnt(0)
; #define MFMA32(a, b, c) __builtin_amdgcn_mfma_f32_32x32x16_bf16((a), (b), (c), 0, 0, 0)
; DI void ret_unit(CParams& P, int l, int u, LAS unsigned char* lds, int tid_, int lane_, int wave_) {
;     ...
;         for (int dt = 0; dt < 8; ++dt) {
;             int ln = lane; asm volatile("" : "+v"(ln));
; #pragma unroll
;             for (int i = 0; i < 16; ++i) St[dt][i] *= g64;
; #pragma unroll
;             for (int ks = 0; ks < 4; ++ks) { const bf16x8 a = frag_tr(Ks, LD, 16 * ks, 32 * dt, ln); St[dt] = MFMA32(a, bv[ks], St[dt]); }
;             asm volatile("" : "+v"(St[dt])); }
	v_mfma_f32_32x32x16_bf16 v[0:15], v[128:131], v[144:147], v[0:15]
	ds_read_b64_tr_b16 v[128:129], v132 offset:50688
	ds_read_b64_tr_b16 v[130:131], v132 offset:52800
	v_mul_f32_e64 v54, v192, v54
	v_mul_f32_e64 v55, v193, v55
	v_mul_f32_e64 v52, v192, v52
	v_mul_f32_e64 v53, v193, v53
	v_pk_mul_f32 v[50:51], v[192:193], v[50:51]
	v_pk_mul_f32 v[48:49], v[194:195], v[48:49]
	v_pk_mul_f32 v[78:79], v[192:193], v[78:79]
	v_pk_mul_f32 v[76:77], v[192:193], v[76:77]
	s_waitcnt lgkmcnt(0)
	v_mfma_f32_32x32x16_bf16 v[0:15], v[128:131], v[148:151], v[0:15]
	ds_read_b64_tr_b16 v[128:129], v132 offset:59136
	ds_read_b64_tr_b16 v[130:131], v132 offset:61248
	v_mul_f32_e64 v74, v192, v74
	v_mul_f32_e64 v75, v193, v75
	v_mul_f32_e64 v72, v192, v72
	v_mul_f32_e64 v73, v193, v73
	v_pk_mul_f32 v[70:71], v[192:193], v[70:71]
	v_pk_mul_f32 v[68:69], v[192:193], v[68:69]
	v_pk_mul_f32 v[66:67], v[192:193], v[66:67]
	v_pk_mul_f32 v[64:65], v[194:195], v[64:65]
	s_waitcnt lgkmcnt(0)
	v_mfma_f32_32x32x16_bf16 v[0:15], v[128:131], v[152:155], v[0:15]
	v_mov_b32_e32 v128, v181
	v_pk_mul_f32 v[94:95], v[192:193], v[94:95]
	v_lshrrev_b32_e32 v130, 2, v128
	v_and_b32_e32 v129, 16, v128
	v_and_b32_e32 v130, 0xffffffb, v130
	v_lshlrev_b32_e32 v128, 3, v128
	v_lshl_add_u32 v129, v129, 1, 0
	v_and_b32_e32 v128, 24, v128
	v_mul_lo_u32 v130, v130, s93
	v_add3_u32 v132, v129, v128, v130
	ds_read_b64_tr_b16 v[128:129], v132 offset:33856
	ds_read_b64_tr_b16 v[130:131], v132 offset:35968
	s_waitcnt lgkmcnt(0)
	v_mfma_f32_32x32x16_bf16 v[16:31], v[128:131], v[176:179], v[16:31]
	ds_read_b64_tr_b16 v[128:129], v132 offset:42304
	ds_read_b64_tr_b16 v[130:131], v132 offset:44416
	v_mul_f32_e64 v92, v192, v92
	v_mul_f32_e64 v93, v193, v93
	v_mul_f32_e64 v90, v192, v90
	v_mul_f32_e64 v91, v193, v91
	v_pk_mul_f32 v[88:89], v[192:193], v[88:89]
	v_pk_mul_f32 v[86:87], v[192:193], v[86:87]
	v_pk_mul_f32 v[84:85], v[192:193], v[84:85]
	v_pk_mul_f32 v[82:83], v[192:193], v[82:83]
	s_waitcnt lgkmcnt(0)
	v_mfma_f32_32x32x16_bf16 v[16:31], v[128:131], v[144:147], v[16:31]
	ds_read_b64_tr_b16 v[128:129], v132 offset:50752
	ds_read_b64_tr_b16 v[130:131], v132 offset:52864
	v_mul_f32_e64 v80, v194, v80
	v_mul_f32_e64 v81, v195, v81
	v_mul_f32_e64 v110, v192, v110
	v_mul_f32_e64 v111, v193, v111
	v_pk_mul_f32 v[108:109], v[192:193], v[108:109]
	v_pk_mul_f32 v[106:107], v[192:193], v[106:107]
	v_pk_mul_f32 v[104:105], v[192:193], v[104:105]
	v_pk_mul_f32 v[102:103], v[192:193], v[102:103]
	s_waitcnt lgkmcnt(0)
	v_mfma_f32_32x32x16_bf16 v[16:31], v[128:131], v[148:151], v[16:31]
	ds_read_b64_tr_b16 v[128:129], v132 offset:59200
	ds_read_b64_tr_b16 v[130:131], v132 offset:61312
	v_mul_f32_e64 v100, v192, v100
	v_mul_f32_e64 v101, v193, v101
	v_mul_f32_e64 v98, v192, v98
	v_mul_f32_e64 v99, v193, v99
	v_pk_mul_f32 v[96:97], v[194:195], v[96:97]
	v_pk_mul_f32 v[126:127], v[192:193], v[126:127]
	v_pk_mul_f32 v[124:125], v[192:193], v[124:125]
	v_pk_mul_f32 v[122:123], v[192:193], v[122:123]
	s_waitcnt lgkmcnt(0)
	v_mfma_f32_32x32x16_bf16 v[16:31], v[128:131], v[152:155], v[16:31]
	v_mov_b32_e32 v128, v181
	v_pk_mul_f32 v[120:121], v[192:193], v[120:121]
	v_lshrrev_b32_e32 v130, 2, v128
	v_and_b32_e32 v129, 16, v128
	v_and_b32_e32 v130, 0xffffffb, v130
	v_lshlrev_b32_e32 v128, 3, v128
	v_lshl_add_u32 v129, v129, 1, 0
	v_and_b32_e32 v128, 24, v128
	v_mul_lo_u32 v130, v130, s93
	v_add3_u32 v132, v129, v128, v130
	ds_read_b64_tr_b16 v[128:129], v132 offset:33920
	ds_read_b64_tr_b16 v[130:131], v132 offset:36032
	s_waitcnt lgkmcnt(0)
	v_mfma_f32_32x32x16_bf16 v[32:47], v[128:131], v[176:179], v[32:47]
	ds_read_b64_tr_b16 v[128:129], v132 offset:42368
	ds_read_b64_tr_b16 v[130:131], v132 offset:44480
	v_mul_f32_e64 v118, v192, v118
	v_mul_f32_e64 v119, v193, v119
	v_mul_f32_e64 v116, v192, v116
	v_mul_f32_e64 v117, v193, v117
	v_pk_mul_f32 v[114:115], v[192:193], v[114:115]
	v_pk_mul_f32 v[112:113], v[194:195], v[112:113]
	s_andn2_b64 vcc, exec, s[66:67]
	s_mov_b32 s57, 0x32201000
	s_waitcnt lgkmcnt(0)
	v_mfma_f32_32x32x16_bf16 v[32:47], v[128:131], v[144:147], v[32:47]
	ds_read_b64_tr_b16 v[128:129], v132 offset:50816
	ds_read_b64_tr_b16 v[130:131], v132 offset:52928
	s_waitcnt lgkmcnt(0)
	v_mfma_f32_32x32x16_bf16 v[32:47], v[128:131], v[148:151], v[32:47]
	ds_read_b64_tr_b16 v[128:129], v132 offset:59264
	ds_read_b64_tr_b16 v[130:131], v132 offset:61376
	s_waitcnt lgkmcnt(0)
	v_mfma_f32_32x32x16_bf16 v[32:47], v[128:131], v[152:155], v[32:47]
	v_mov_b32_e32 v128, v181
	s_nop 0
	v_lshrrev_b32_e32 v130, 2, v128
	v_and_b32_e32 v129, 16, v128
	v_and_b32_e32 v130, 0xffffffb, v130
	v_lshlrev_b32_e32 v128, 3, v128
	v_lshl_add_u32 v129, v129, 1, 0
	v_and_b32_e32 v128, 24, v128
	v_mul_lo_u32 v130, v130, s93
	v_add3_u32 v132, v129, v128, v130
	ds_read_b64_tr_b16 v[128:129], v132 offset:33984
	ds_read_b64_tr_b16 v[130:131], v132 offset:36096
	s_waitcnt lgkmcnt(0)
	v_mfma_f32_32x32x16_bf16 v[48:63], v[128:131], v[176:179], v[48:63]
	ds_read_b64_tr_b16 v[128:129], v132 offset:42432
	ds_read_b64_tr_b16 v[130:131], v132 offset:44544
	s_waitcnt lgkmcnt(0)
	v_mfma_f32_32x32x16_bf16 v[48:63], v[128:131], v[144:147], v[48:63]
	ds_read_b64_tr_b16 v[128:129], v132 offset:50880
	ds_read_b64_tr_b16 v[130:131], v132 offset:52992
	s_waitcnt lgkmcnt(0)
; #define MFMA32(a, b, c) __builtin_amdgcn_mfma_f32_32x32x16_bf16((a), (b), (c), 0, 0, 0)
; #define RET_FRESH() int tid = tid0; asm volatile("" : "+v"(tid)); const int lane = tid & 63, r = lane & 31, h = lane >> 5; (void)r; (void)h; (void)tid
; #define RET_VMWAIT() asm volatile("s_waitcnt vmcnt(0)" ::: "memory")
; DI void ret_unit(CParams& P, int l, int u, LAS unsigned char* lds, int tid_, int lane_, int wave_) {
;     ...
;         for (int dt = 0; dt < 8; ++dt) {
;             int ln = lane; asm volatile("" : "+v"(ln));
; #pragma unroll
;             for (int i = 0; i < 16; ++i) St[dt][i] *= g64;
; #pragma unroll
;             for (int ks = 0; ks < 4; ++ks) { const bf16x8 a = frag_tr(Ks, LD, 16 * ks, 32 * dt, ln); St[dt] = MFMA32(a, bv[ks], St[dt]); }
;             asm volatile("" : "+v"(St[dt])); }
;         }
;         RET_VMWAIT();
;         __syncthreads();
;         { RET_FRESH(); if (n + 1 < 32) { RET_DMA(1, n + 1); RET_DMA(2, n + 1); } }
	v_mfma_f32_32x32x16_bf16 v[48:63], v[128:131], v[148:151], v[48:63]
	ds_read_b64_tr_b16 v[128:129], v132 offset:59328
	ds_read_b64_tr_b16 v[130:131], v132 offset:61440
	s_waitcnt lgkmcnt(0)
	v_mfma_f32_32x32x16_bf16 v[48:63], v[128:131], v[152:155], v[48:63]
	v_mov_b32_e32 v128, v181
	s_nop 0
	v_lshrrev_b32_e32 v130, 2, v128
	v_and_b32_e32 v129, 16, v128
	v_and_b32_e32 v130, 0xffffffb, v130
	v_lshlrev_b32_e32 v128, 3, v128
	v_lshl_add_u32 v129, v129, 1, 0
	v_and_b32_e32 v128, 24, v128
	v_mul_lo_u32 v130, v130, s93
	v_add3_u32 v132, v129, v128, v130
	ds_read_b64_tr_b16 v[128:129], v132 offset:34048
	ds_read_b64_tr_b16 v[130:131], v132 offset:36160
	s_waitcnt lgkmcnt(0)
	v_mfma_f32_32x32x16_bf16 v[64:79], v[128:131], v[176:179], v[64:79]
	ds_read_b64_tr_b16 v[128:129], v132 offset:42496
	ds_read_b64_tr_b16 v[130:131], v132 offset:44608
	s_waitcnt lgkmcnt(0)
	v_mfma_f32_32x32x16_bf16 v[64:79], v[128:131], v[144:147], v[64:79]
	ds_read_b64_tr_b16 v[128:129], v132 offset:50944
	ds_read_b64_tr_b16 v[130:131], v132 offset:53056
	s_waitcnt lgkmcnt(0)
	v_mfma_f32_32x32x16_bf16 v[64:79], v[128:131], v[148:151], v[64:79]
	ds_read_b64_tr_b16 v[128:129], v132 offset:59392
	ds_read_b64_tr_b16 v[130:131], v132 offset:61504
	s_waitcnt lgkmcnt(0)
	v_mfma_f32_32x32x16_bf16 v[64:79], v[128:131], v[152:155], v[64:79]
	v_mov_b32_e32 v128, v181
	s_nop 0
	v_lshrrev_b32_e32 v130, 2, v128
	v_and_b32_e32 v129, 16, v128
	v_and_b32_e32 v130, 0xffffffb, v130
	v_lshlrev_b32_e32 v128, 3, v128
	v_lshl_add_u32 v129, v129, 1, 0
	v_and_b32_e32 v128, 24, v128
	v_mul_lo_u32 v130, v130, s93
	v_add3_u32 v132, v129, v128, v130
	ds_read_b64_tr_b16 v[128:129], v132 offset:34112
	ds_read_b64_tr_b16 v[130:131], v132 offset:36224
	s_waitcnt lgkmcnt(0)
	v_mfma_f32_32x32x16_bf16 v[80:95], v[128:131], v[176:179], v[80:95]
	ds_read_b64_tr_b16 v[128:129], v132 offset:42560
	ds_read_b64_tr_b16 v[130:131], v132 offset:44672
	s_waitcnt lgkmcnt(0)
	v_mfma_f32_32x32x16_bf16 v[80:95], v[128:131], v[144:147], v[80:95]
	ds_read_b64_tr_b16 v[128:129], v132 offset:51008
	ds_read_b64_tr_b16 v[130:131], v132 offset:53120
	s_waitcnt lgkmcnt(0)
	v_mfma_f32_32x32x16_bf16 v[80:95], v[128:131], v[148:151], v[80:95]
	ds_read_b64_tr_b16 v[128:129], v132 offset:59456
	ds_read_b64_tr_b16 v[130:131], v132 offset:61568
	s_waitcnt lgkmcnt(0)
	v_mfma_f32_32x32x16_bf16 v[80:95], v[128:131], v[152:155], v[80:95]
	v_mov_b32_e32 v128, v181
	s_nop 0
	v_lshrrev_b32_e32 v130, 2, v128
	v_and_b32_e32 v129, 16, v128
	v_and_b32_e32 v130, 0xffffffb, v130
	v_lshlrev_b32_e32 v128, 3, v128
	v_lshl_add_u32 v129, v129, 1, 0
	v_and_b32_e32 v128, 24, v128
	v_mul_lo_u32 v130, v130, s93
	v_add3_u32 v132, v129, v128, v130
	ds_read_b64_tr_b16 v[128:129], v132 offset:34176
	ds_read_b64_tr_b16 v[130:131], v132 offset:36288
	s_waitcnt lgkmcnt(0)
	v_mfma_f32_32x32x16_bf16 v[96:111], v[128:131], v[176:179], v[96:111]
	ds_read_b64_tr_b16 v[128:129], v132 offset:42624
	ds_read_b64_tr_b16 v[130:131], v132 offset:44736
	s_waitcnt lgkmcnt(0)
	v_mfma_f32_32x32x16_bf16 v[96:111], v[128:131], v[144:147], v[96:111]
	ds_read_b64_tr_b16 v[128:129], v132 offset:51072
	ds_read_b64_tr_b16 v[130:131], v132 offset:53184
	s_waitcnt lgkmcnt(0)
	v_mfma_f32_32x32x16_bf16 v[96:111], v[128:131], v[148:151], v[96:111]
	ds_read_b64_tr_b16 v[128:129], v132 offset:59520
	ds_read_b64_tr_b16 v[130:131], v132 offset:61632
	s_waitcnt lgkmcnt(0)
	v_mfma_f32_32x32x16_bf16 v[96:111], v[128:131], v[152:155], v[96:111]
	s_nop 0
	v_lshrrev_b32_e32 v129, 2, v181
	v_and_b32_e32 v128, 16, v181
	v_and_b32_e32 v129, 0xffffffb, v129
	v_lshlrev_b32_e32 v130, 3, v181
	v_lshl_add_u32 v128, v128, 1, 0
	v_and_b32_e32 v130, 24, v130
	v_mul_lo_u32 v129, v129, s93
	v_add3_u32 v132, v128, v130, v129
	ds_read_b64_tr_b16 v[128:129], v132 offset:34240
	ds_read_b64_tr_b16 v[130:131], v132 offset:36352
	s_waitcnt lgkmcnt(0)
	v_mfma_f32_32x32x16_bf16 v[112:127], v[128:131], v[176:179], v[112:127]
	ds_read_b64_tr_b16 v[128:129], v132 offset:42688
	ds_read_b64_tr_b16 v[130:131], v132 offset:44800
	s_waitcnt lgkmcnt(0)
	v_mfma_f32_32x32x16_bf16 v[112:127], v[128:131], v[144:147], v[112:127]
	ds_read_b64_tr_b16 v[128:129], v132 offset:51136
	ds_read_b64_tr_b16 v[130:131], v132 offset:53248
	s_waitcnt lgkmcnt(0)
	v_mfma_f32_32x32x16_bf16 v[112:127], v[128:131], v[148:151], v[112:127]
	ds_read_b64_tr_b16 v[128:129], v132 offset:59584
	ds_read_b64_tr_b16 v[130:131], v132 offset:61696
	s_waitcnt lgkmcnt(0)
	v_mfma_f32_32x32x16_bf16 v[112:127], v[128:131], v[152:155], v[112:127]
	s_waitcnt vmcnt(0)
	v_mov_b32_e32 v128, v180
	s_barrier
	s_cbranch_vccnz .LBB0_389
	s_and_b64 vcc, exec, s[8:9]
	s_cbranch_vccnz .LBB0_389
	s_lshl_b32 s8, s22, 6
	v_readlane_b32 s9, v254, 11
	s_add_i32 s8, s8, s9
	s_mul_hi_i32 s9, s8, 0x6000
	s_mulk_i32 s8, 0x6000
	v_readlane_b32 s66, v255, 38
	s_add_u32 s66, s66, s8
	v_readlane_b32 s8, v255, 39
	s_addc_u32 s67, s8, s9
	v_and_b32_e32 v128, 63, v128
	v_readlane_b32 s88, v255, 37
	s_add_u32 s8, s66, 0x1a203800
	s_addc_u32 s9, s67, 0
	v_add_u32_e32 v128, s88, v128
	v_mov_b32_e32 v130, v128
	v_readlane_b32 vcc_lo, v255, 43
	s_mov_b32 vcc_hi, s7

;     __device__ __forceinline__ bool next(int i, Unit& u) const {
;     ...
;         else if (c >= 32) { if (i < 8) L = i * 224 + (c - 32); else if (i == 8 && c < 96) L = 1984 + (c - 32); else return false; }
;         else { if (i < 6) L = 1792 + i * 32 + c; else return false; }
.LBB0_412:
	v_readlane_b32 s14, v254, 9
	v_readlane_b32 s15, v254, 10
	s_add_i32 s40, s2, 1
	s_and_b64 vcc, exec, s[14:15]
	s_cbranch_vccz .LBB0_415
	s_mov_b64 s[26:27], 0
	s_cmp_lt_u32 s2, 3
	s_mov_b64 s[14:15], 0
	s_cbranch_scc0 .LBB0_416
	s_lshl_b32 s3, s40, 5
	v_readlane_b32 s14, v254, 22
	s_add_i32 s3, s14, s3
	s_mov_b64 s[14:15], -1
	s_branch .LBB0_416

;     __device__ __forceinline__ bool next(int i, Unit& u) const {
;     ...
;         else if (c >= 32) { if (i < 8) L = i * 224 + (c - 32); else if (i == 8 && c < 96) L = 1984 + (c - 32); else return false; }
.LBB0_416:
	s_and_b64 vcc, exec, s[26:27]
	s_cbranch_vccz .LBB0_421
	s_cmp_gt_u32 s2, 6
	s_mov_b64 s[26:27], -1
	s_cbranch_scc0 .LBB0_419
	s_cmp_eq_u32 s40, 8
	v_readlane_b32 s14, v254, 23
	s_cselect_b64 s[2:3], -1, 0
	v_readlane_b32 s15, v254, 24
	s_and_b64 s[14:15], s[14:15], s[2:3]
	s_mov_b64 s[26:27], 0
	v_readlane_b32 s3, v254, 25
	s_cmp_eq_u32 s40, 9
	s_cbranch_scc0 .LBB0_421
	s_cmp_lt_u32 s69, 96
	s_cbranch_scc0 .LBB0_421
	s_cmp_ge_u32 s69, 32
	s_cbranch_scc0 .LBB0_421
	s_add_i32 s3, s3, -64
	s_mov_b64 s[14:15], -1
	s_branch .LBB0_421
